# v33 + gated-merge epilogue math rewritten with packed f32 ops and uniform skip of the unused denominator path on the final sub-unit
# speedup vs baseline: 1.0037x; 1.0037x over previous
; #define GAS __attribute__((address_space(1)))
; __device__ __forceinline__ unsigned cvt_pk_bf16(float lo, float hi) { unsigned r; asm volatile("v_cvt_pk_bf16_f32 %0, %1, %2" : "=v"(r) : "v"(lo), "v"(hi)); return r; }
;     __device__ __forceinline__ void operator()(f32x4 (&acc)[2][2][4][2], const Unit& u, int wr, int wc, int fr, int fq) const {
;         int row0 = u.pm * BM + wr * 64 + fr, col0 = u.pn * BM + wc * 32 + 8 * fq;
;         const bool fin = u.z == 2;
;         const int offn = O_GATE + u.z * D, offd = O_GATE + (fin ? 2 : u.z + 1) * D;
; #pragma unroll
;         for (int ai = 0; ai < 2; ++ai) {
;             int rowi = row0 + ai * HALF; asm volatile("" : "+v"(rowi));
;             u32x4 zn[4][2], zd[4][2];
; #pragma unroll
;             for (int m = 0; m < 4; ++m)
; #pragma unroll
;                 for (int bj = 0; bj < 2; ++bj) { const GAS bf16_t* zp = Z + (size_t)(rowi + m * 16) * DIN + col0 + bj * HALF; zn[m][bj] = *(const GAS u32x4*)(zp + offn); zd[m][bj] = *(const GAS u32x4*)(zp + offd); }
; #pragma unroll
;             for (int m = 0; m < 4; ++m) {
; #pragma unroll
;                 for (int bj = 0; bj < 2; ++bj) {
;                     const unsigned nn[4] = {zn[m][bj].x, zn[m][bj].y, zn[m][bj].z, zn[m][bj].w}, dd[4] = {zd[m][bj].x, zd[m][bj].y, zd[m][bj].z, zd[m][bj].w};
;                     float f[8];
; #pragma unroll
;                     for (int e = 0; e < 4; ++e) {
;                         const float n0 = __builtin_amdgcn_rcpf(1.0f + __expf(-bflo(nn[e]))), n1 = __builtin_amdgcn_rcpf(1.0f + __expf(-bfhi(nn[e])));
;                         const float d0 = fin ? 1.0f : 1.0f + __expf(-bflo(dd[e])), d1 = fin ? 1.0f : 1.0f + __expf(-bfhi(dd[e]));
;                         f[2 * e] = n0 * d0; f[2 * e + 1] = n1 * d1; }
; #pragma unroll
;                     for (int n = 0; n < 2; ++n)
; #pragma unroll
;                         for (int e = 0; e < 4; ++e) acc[ai][bj][m][n][e] *= f[4 * n + e];
;                     if (fin) { u32x4 w; w.x = cvt_pk_bf16(acc[ai][bj][m][0][0], acc[ai][bj][m][0][1]); w.y = cvt_pk_bf16(acc[ai][bj][m][0][2], acc[ai][bj][m][0][3]);
;                         w.z = cvt_pk_bf16(acc[ai][bj][m][1][0], acc[ai][bj][m][1][1]); w.w = cvt_pk_bf16(acc[ai][bj][m][1][2], acc[ai][bj][m][1][3]);
;                         *(GAS u32x4*)(MG + (size_t)(rowi + m * 16) * D + col0 + bj * HALF) = w; } }
.LBB0_1131:
	s_mov_b32 s100, 0xbfb8aa3b
	s_mov_b32 s101, 1.0
	v_lshl_or_b32 v216, s18, 8, v246
	s_lshl_b32 s4, s4, 11
	s_add_i32 s5, s4, 0x2000
	v_lshl_add_u32 v248, s10, 8, v1
	v_ashrrev_i32_e32 v217, 31, v216
	s_and_b64 s[24:25], s[8:9], exec
	v_mov_b32_e32 v226, v248
	v_lshl_add_u64 v[218:219], v[216:217], 1, s[44:45]
	s_cselect_b32 s24, 0x2800, s5
	s_ashr_i32 s5, s4, 31
	s_movk_i32 s7, 0x3000
	v_mad_i64_i32 v[130:131], s[10:11], v226, s74, v[218:219]
	s_lshl_b64 s[10:11], s[4:5], 1
	s_nop 0
	v_lshl_add_u64 v[132:133], v[130:131], 0, s[10:11]
	v_add_co_u32_e32 v132, vcc, s7, v132
	s_ashr_i32 s25, s24, 31
	s_nop 0
	v_addc_co_u32_e32 v133, vcc, 0, v133, vcc
	global_load_dwordx4 v[190:193], v[132:133], off
	s_lshl_b64 s[24:25], s[24:25], 1
	v_lshl_add_u64 v[130:131], v[130:131], 0, s[24:25]
	global_load_dwordx4 v[186:189], v[130:131], off
	global_load_dwordx4 v[182:185], v[132:133], off offset:256
	global_load_dwordx4 v[178:181], v[130:131], off offset:256
	v_add_u32_e32 v224, 16, v226
	v_mad_i64_i32 v[130:131], s[4:5], v224, s74, v[218:219]
	v_lshl_add_u64 v[132:133], v[130:131], 0, s[10:11]
	v_add_co_u32_e32 v132, vcc, s7, v132
	v_lshl_add_u64 v[130:131], v[130:131], 0, s[24:25]
	s_nop 0
	v_addc_co_u32_e32 v133, vcc, 0, v133, vcc
	v_add_u32_e32 v222, 32, v226
	global_load_dwordx4 v[174:177], v[132:133], off
	global_load_dwordx4 v[170:173], v[130:131], off
	global_load_dwordx4 v[166:169], v[132:133], off offset:256
	global_load_dwordx4 v[162:165], v[130:131], off offset:256
	v_mad_i64_i32 v[130:131], s[4:5], v222, s74, v[218:219]
	v_lshl_add_u64 v[132:133], v[130:131], 0, s[10:11]
	v_add_co_u32_e32 v132, vcc, s7, v132
	v_lshl_add_u64 v[130:131], v[130:131], 0, s[24:25]
	s_nop 0
	v_addc_co_u32_e32 v133, vcc, 0, v133, vcc
	v_add_u32_e32 v220, 48, v226
	global_load_dwordx4 v[158:161], v[132:133], off
	global_load_dwordx4 v[154:157], v[130:131], off
	global_load_dwordx4 v[150:153], v[132:133], off offset:256
	global_load_dwordx4 v[146:149], v[130:131], off offset:256
	v_mad_i64_i32 v[130:131], s[4:5], v220, s74, v[218:219]
	v_lshl_add_u64 v[132:133], v[130:131], 0, s[10:11]
	v_add_co_u32_e32 v132, vcc, s7, v132
	v_lshl_add_u64 v[130:131], v[130:131], 0, s[24:25]
	s_nop 0
	v_addc_co_u32_e32 v133, vcc, 0, v133, vcc
	global_load_dwordx4 v[142:145], v[132:133], off
	global_load_dwordx4 v[138:141], v[130:131], off
	global_load_dwordx4 v[134:137], v[132:133], off offset:256
	s_nop 0
	global_load_dwordx4 v[130:133], v[130:131], off offset:256
	v_ashrrev_i32_e32 v227, 31, v226
	v_lshlrev_b64 v[226:227], 12, v[226:227]
	s_andn2_b64 vcc, exec, s[8:9]
	s_waitcnt vmcnt(0)
	v_lshlrev_b32_e32 v228, 16, v190
	v_and_b32_e32 v229, 0xffff0000, v190
	v_lshlrev_b32_e32 v230, 16, v191
	v_and_b32_e32 v231, 0xffff0000, v191
	v_lshlrev_b32_e32 v232, 16, v192
	v_and_b32_e32 v233, 0xffff0000, v192
	v_lshlrev_b32_e32 v234, 16, v193
	v_and_b32_e32 v235, 0xffff0000, v193
	v_pk_mul_f32 v[228:229], v[228:229], s[100:101] op_sel_hi:[1,0]
	v_pk_mul_f32 v[230:231], v[230:231], s[100:101] op_sel_hi:[1,0]
	v_pk_mul_f32 v[232:233], v[232:233], s[100:101] op_sel_hi:[1,0]
	v_pk_mul_f32 v[234:235], v[234:235], s[100:101] op_sel_hi:[1,0]
	v_exp_f32_e32 v228, v228
	v_exp_f32_e32 v229, v229
	v_exp_f32_e32 v230, v230
	v_exp_f32_e32 v231, v231
	v_exp_f32_e32 v232, v232
	v_exp_f32_e32 v233, v233
	v_exp_f32_e32 v234, v234
	v_exp_f32_e32 v235, v235
	v_pk_add_f32 v[228:229], v[228:229], s[100:101] op_sel:[0,1]
	v_pk_add_f32 v[230:231], v[230:231], s[100:101] op_sel:[0,1]
	v_pk_add_f32 v[232:233], v[232:233], s[100:101] op_sel:[0,1]
	v_pk_add_f32 v[234:235], v[234:235], s[100:101] op_sel:[0,1]
	v_rcp_f32_e32 v228, v228
	v_rcp_f32_e32 v229, v229
	v_rcp_f32_e32 v230, v230
	v_rcp_f32_e32 v231, v231
	v_rcp_f32_e32 v232, v232
	v_rcp_f32_e32 v233, v233
	v_rcp_f32_e32 v234, v234
	v_rcp_f32_e32 v235, v235
	s_cmp_lg_u64 s[8:9], 0
	s_cbranch_scc1 .Lme_fin0
	v_lshlrev_b32_e32 v236, 16, v186
	v_and_b32_e32 v237, 0xffff0000, v186
	v_lshlrev_b32_e32 v238, 16, v187
	v_and_b32_e32 v239, 0xffff0000, v187
	v_lshlrev_b32_e32 v240, 16, v188
	v_and_b32_e32 v241, 0xffff0000, v188
	v_lshlrev_b32_e32 v242, 16, v189
	v_and_b32_e32 v243, 0xffff0000, v189
	v_pk_mul_f32 v[236:237], v[236:237], s[100:101] op_sel_hi:[1,0]
	v_pk_mul_f32 v[238:239], v[238:239], s[100:101] op_sel_hi:[1,0]
	v_pk_mul_f32 v[240:241], v[240:241], s[100:101] op_sel_hi:[1,0]
	v_pk_mul_f32 v[242:243], v[242:243], s[100:101] op_sel_hi:[1,0]
	v_exp_f32_e32 v236, v236
	v_exp_f32_e32 v237, v237
	v_exp_f32_e32 v238, v238
	v_exp_f32_e32 v239, v239
	v_exp_f32_e32 v240, v240
	v_exp_f32_e32 v241, v241
	v_exp_f32_e32 v242, v242
	v_exp_f32_e32 v243, v243
	v_pk_add_f32 v[236:237], v[236:237], s[100:101] op_sel:[0,1]
	v_pk_add_f32 v[238:239], v[238:239], s[100:101] op_sel:[0,1]
	v_pk_add_f32 v[240:241], v[240:241], s[100:101] op_sel:[0,1]
	v_pk_add_f32 v[242:243], v[242:243], s[100:101] op_sel:[0,1]
	v_pk_mul_f32 v[228:229], v[228:229], v[236:237]
	v_pk_mul_f32 v[230:231], v[230:231], v[238:239]
	v_pk_mul_f32 v[232:233], v[232:233], v[240:241]
	v_pk_mul_f32 v[234:235], v[234:235], v[242:243]
.Lme_fin0:
	v_pk_mul_f32 v[126:127], v[126:127], v[228:229]
	v_pk_mul_f32 v[128:129], v[128:129], v[230:231]
	v_pk_mul_f32 v[122:123], v[122:123], v[232:233]
	v_pk_mul_f32 v[124:125], v[124:125], v[234:235]
	v_cndmask_b32_e64 v186, 0, 1, s[8:9]
	v_cmp_ne_u32_e64 s[42:43], 1, v186
	v_lshl_add_u64 v[186:187], s[48:49], 0, v[226:227]
	v_lshl_add_u64 v[186:187], v[216:217], 1, v[186:187]
	s_cbranch_vccnz .LBB0_1133
	v_cvt_pk_bf16_f32 v188, v126, v127
	v_cvt_pk_bf16_f32 v189, v128, v129
	v_cvt_pk_bf16_f32 v190, v122, v123
	v_cvt_pk_bf16_f32 v191, v124, v125
	global_store_dwordx4 v[186:187], v[188:191], off
; #define GAS __attribute__((address_space(1)))
; __device__ __forceinline__ unsigned cvt_pk_bf16(float lo, float hi) { unsigned r; asm volatile("v_cvt_pk_bf16_f32 %0, %1, %2" : "=v"(r) : "v"(lo), "v"(hi)); return r; }
;     __device__ __forceinline__ void operator()(f32x4 (&acc)[2][2][4][2], const Unit& u, int wr, int wc, int fr, int fq) const {
;     ...
;             for (int m = 0; m < 4; ++m) {
; #pragma unroll
;                 for (int bj = 0; bj < 2; ++bj) {
;                     const unsigned nn[4] = {zn[m][bj].x, zn[m][bj].y, zn[m][bj].z, zn[m][bj].w}, dd[4] = {zd[m][bj].x, zd[m][bj].y, zd[m][bj].z, zd[m][bj].w};
;                     float f[8];
; #pragma unroll
;                     for (int e = 0; e < 4; ++e) {
;                         const float n0 = __builtin_amdgcn_rcpf(1.0f + __expf(-bflo(nn[e]))), n1 = __builtin_amdgcn_rcpf(1.0f + __expf(-bfhi(nn[e])));
;                         const float d0 = fin ? 1.0f : 1.0f + __expf(-bflo(dd[e])), d1 = fin ? 1.0f : 1.0f + __expf(-bfhi(dd[e]));
;                         f[2 * e] = n0 * d0; f[2 * e + 1] = n1 * d1; }
; #pragma unroll
;                     for (int n = 0; n < 2; ++n)
; #pragma unroll
;                         for (int e = 0; e < 4; ++e) acc[ai][bj][m][n][e] *= f[4 * n + e];
;                     if (fin) { u32x4 w; w.x = cvt_pk_bf16(acc[ai][bj][m][0][0], acc[ai][bj][m][0][1]); w.y = cvt_pk_bf16(acc[ai][bj][m][0][2], acc[ai][bj][m][0][3]);
;                         w.z = cvt_pk_bf16(acc[ai][bj][m][1][0], acc[ai][bj][m][1][1]); w.w = cvt_pk_bf16(acc[ai][bj][m][1][2], acc[ai][bj][m][1][3]);
;                         *(GAS u32x4*)(MG + (size_t)(rowi + m * 16) * D + col0 + bj * HALF) = w; } }
.LBB0_1133:
	s_nop 1
	v_lshlrev_b32_e32 v228, 16, v182
	v_and_b32_e32 v229, 0xffff0000, v182
	v_lshlrev_b32_e32 v230, 16, v183
	v_and_b32_e32 v231, 0xffff0000, v183
	v_lshlrev_b32_e32 v232, 16, v184
	v_and_b32_e32 v233, 0xffff0000, v184
	v_lshlrev_b32_e32 v234, 16, v185
	v_and_b32_e32 v235, 0xffff0000, v185
	v_pk_mul_f32 v[228:229], v[228:229], s[100:101] op_sel_hi:[1,0]
	v_pk_mul_f32 v[230:231], v[230:231], s[100:101] op_sel_hi:[1,0]
	v_pk_mul_f32 v[232:233], v[232:233], s[100:101] op_sel_hi:[1,0]
	v_pk_mul_f32 v[234:235], v[234:235], s[100:101] op_sel_hi:[1,0]
	v_exp_f32_e32 v228, v228
	v_exp_f32_e32 v229, v229
	v_exp_f32_e32 v230, v230
	v_exp_f32_e32 v231, v231
	v_exp_f32_e32 v232, v232
	v_exp_f32_e32 v233, v233
	v_exp_f32_e32 v234, v234
	v_exp_f32_e32 v235, v235
	v_pk_add_f32 v[228:229], v[228:229], s[100:101] op_sel:[0,1]
	v_pk_add_f32 v[230:231], v[230:231], s[100:101] op_sel:[0,1]
	v_pk_add_f32 v[232:233], v[232:233], s[100:101] op_sel:[0,1]
	v_pk_add_f32 v[234:235], v[234:235], s[100:101] op_sel:[0,1]
	v_rcp_f32_e32 v228, v228
	v_rcp_f32_e32 v229, v229
	v_rcp_f32_e32 v230, v230
	v_rcp_f32_e32 v231, v231
	v_rcp_f32_e32 v232, v232
	v_rcp_f32_e32 v233, v233
	v_rcp_f32_e32 v234, v234
	v_rcp_f32_e32 v235, v235
	s_cmp_lg_u64 s[8:9], 0
	s_cbranch_scc1 .Lme_fin1
	v_lshlrev_b32_e32 v236, 16, v178
	v_and_b32_e32 v237, 0xffff0000, v178
	v_lshlrev_b32_e32 v238, 16, v179
	v_and_b32_e32 v239, 0xffff0000, v179
	v_lshlrev_b32_e32 v240, 16, v180
	v_and_b32_e32 v241, 0xffff0000, v180
	v_lshlrev_b32_e32 v242, 16, v181
	v_and_b32_e32 v243, 0xffff0000, v181
	v_pk_mul_f32 v[236:237], v[236:237], s[100:101] op_sel_hi:[1,0]
	v_pk_mul_f32 v[238:239], v[238:239], s[100:101] op_sel_hi:[1,0]
	v_pk_mul_f32 v[240:241], v[240:241], s[100:101] op_sel_hi:[1,0]
	v_pk_mul_f32 v[242:243], v[242:243], s[100:101] op_sel_hi:[1,0]
	v_exp_f32_e32 v236, v236
	v_exp_f32_e32 v237, v237
	v_exp_f32_e32 v238, v238
	v_exp_f32_e32 v239, v239
	v_exp_f32_e32 v240, v240
	v_exp_f32_e32 v241, v241
	v_exp_f32_e32 v242, v242
	v_exp_f32_e32 v243, v243
	v_pk_add_f32 v[236:237], v[236:237], s[100:101] op_sel:[0,1]
	v_pk_add_f32 v[238:239], v[238:239], s[100:101] op_sel:[0,1]
	v_pk_add_f32 v[240:241], v[240:241], s[100:101] op_sel:[0,1]
	v_pk_add_f32 v[242:243], v[242:243], s[100:101] op_sel:[0,1]
	v_pk_mul_f32 v[228:229], v[228:229], v[236:237]
	v_pk_mul_f32 v[230:231], v[230:231], v[238:239]
	v_pk_mul_f32 v[232:233], v[232:233], v[240:241]
	v_pk_mul_f32 v[234:235], v[234:235], v[242:243]
.Lme_fin1:
	v_pk_mul_f32 v[94:95], v[94:95], v[228:229]
	v_pk_mul_f32 v[96:97], v[96:97], v[230:231]
	v_pk_mul_f32 v[90:91], v[90:91], v[232:233]
	v_pk_mul_f32 v[92:93], v[92:93], v[234:235]
	s_and_b64 vcc, exec, s[42:43]
	s_cbranch_vccnz .LBB0_1135
	v_cvt_pk_bf16_f32 v178, v94, v95
	v_cvt_pk_bf16_f32 v179, v96, v97
	v_cvt_pk_bf16_f32 v180, v90, v91
	v_cvt_pk_bf16_f32 v181, v92, v93
	global_store_dwordx4 v[186:187], v[178:181], off offset:256
.LBB0_1135:
	s_nop 1
	v_lshlrev_b32_e32 v228, 16, v174
	v_and_b32_e32 v229, 0xffff0000, v174
	v_lshlrev_b32_e32 v230, 16, v175
	v_and_b32_e32 v231, 0xffff0000, v175
	v_lshlrev_b32_e32 v232, 16, v176
	v_and_b32_e32 v233, 0xffff0000, v176
	v_lshlrev_b32_e32 v234, 16, v177
	v_and_b32_e32 v235, 0xffff0000, v177
	v_pk_mul_f32 v[228:229], v[228:229], s[100:101] op_sel_hi:[1,0]
	v_pk_mul_f32 v[230:231], v[230:231], s[100:101] op_sel_hi:[1,0]
	v_pk_mul_f32 v[232:233], v[232:233], s[100:101] op_sel_hi:[1,0]
	v_pk_mul_f32 v[234:235], v[234:235], s[100:101] op_sel_hi:[1,0]
	v_exp_f32_e32 v228, v228
	v_exp_f32_e32 v229, v229
	v_exp_f32_e32 v230, v230
	v_exp_f32_e32 v231, v231
	v_exp_f32_e32 v232, v232
	v_exp_f32_e32 v233, v233
	v_exp_f32_e32 v234, v234
	v_exp_f32_e32 v235, v235
	v_pk_add_f32 v[228:229], v[228:229], s[100:101] op_sel:[0,1]
	v_pk_add_f32 v[230:231], v[230:231], s[100:101] op_sel:[0,1]
	v_pk_add_f32 v[232:233], v[232:233], s[100:101] op_sel:[0,1]
	v_pk_add_f32 v[234:235], v[234:235], s[100:101] op_sel:[0,1]
	v_rcp_f32_e32 v228, v228
	v_rcp_f32_e32 v229, v229
	v_rcp_f32_e32 v230, v230
	v_rcp_f32_e32 v231, v231
	v_rcp_f32_e32 v232, v232
	v_rcp_f32_e32 v233, v233
	v_rcp_f32_e32 v234, v234
	v_rcp_f32_e32 v235, v235
	s_cmp_lg_u64 s[8:9], 0
	s_cbranch_scc1 .Lme_fin2
	v_lshlrev_b32_e32 v236, 16, v170
	v_and_b32_e32 v237, 0xffff0000, v170
	v_lshlrev_b32_e32 v238, 16, v171
	v_and_b32_e32 v239, 0xffff0000, v171
	v_lshlrev_b32_e32 v240, 16, v172
	v_and_b32_e32 v241, 0xffff0000, v172
	v_lshlrev_b32_e32 v242, 16, v173
	v_and_b32_e32 v243, 0xffff0000, v173
	v_pk_mul_f32 v[236:237], v[236:237], s[100:101] op_sel_hi:[1,0]
	v_pk_mul_f32 v[238:239], v[238:239], s[100:101] op_sel_hi:[1,0]
	v_pk_mul_f32 v[240:241], v[240:241], s[100:101] op_sel_hi:[1,0]
	v_pk_mul_f32 v[242:243], v[242:243], s[100:101] op_sel_hi:[1,0]
	v_exp_f32_e32 v236, v236
	v_exp_f32_e32 v237, v237
	v_exp_f32_e32 v238, v238
	v_exp_f32_e32 v239, v239
	v_exp_f32_e32 v240, v240
	v_exp_f32_e32 v241, v241
	v_exp_f32_e32 v242, v242
	v_exp_f32_e32 v243, v243
	v_pk_add_f32 v[236:237], v[236:237], s[100:101] op_sel:[0,1]
	v_pk_add_f32 v[238:239], v[238:239], s[100:101] op_sel:[0,1]
	v_pk_add_f32 v[240:241], v[240:241], s[100:101] op_sel:[0,1]
	v_pk_add_f32 v[242:243], v[242:243], s[100:101] op_sel:[0,1]
	v_pk_mul_f32 v[228:229], v[228:229], v[236:237]
	v_pk_mul_f32 v[230:231], v[230:231], v[238:239]
	v_pk_mul_f32 v[232:233], v[232:233], v[240:241]
	v_pk_mul_f32 v[234:235], v[234:235], v[242:243]
; #define GAS __attribute__((address_space(1)))
; __device__ __forceinline__ unsigned cvt_pk_bf16(float lo, float hi) { unsigned r; asm volatile("v_cvt_pk_bf16_f32 %0, %1, %2" : "=v"(r) : "v"(lo), "v"(hi)); return r; }
;     __device__ __forceinline__ void operator()(f32x4 (&acc)[2][2][4][2], const Unit& u, int wr, int wc, int fr, int fq) const {
;     ...
;             for (int m = 0; m < 4; ++m) {
; #pragma unroll
;                 for (int bj = 0; bj < 2; ++bj) {
;                     const unsigned nn[4] = {zn[m][bj].x, zn[m][bj].y, zn[m][bj].z, zn[m][bj].w}, dd[4] = {zd[m][bj].x, zd[m][bj].y, zd[m][bj].z, zd[m][bj].w};
;                     float f[8];
; #pragma unroll
;                     for (int e = 0; e < 4; ++e) {
;                         const float n0 = __builtin_amdgcn_rcpf(1.0f + __expf(-bflo(nn[e]))), n1 = __builtin_amdgcn_rcpf(1.0f + __expf(-bfhi(nn[e])));
;                         const float d0 = fin ? 1.0f : 1.0f + __expf(-bflo(dd[e])), d1 = fin ? 1.0f : 1.0f + __expf(-bfhi(dd[e]));
;                         f[2 * e] = n0 * d0; f[2 * e + 1] = n1 * d1; }
; #pragma unroll
;                     for (int n = 0; n < 2; ++n)
; #pragma unroll
;                         for (int e = 0; e < 4; ++e) acc[ai][bj][m][n][e] *= f[4 * n + e];
;                     if (fin) { u32x4 w; w.x = cvt_pk_bf16(acc[ai][bj][m][0][0], acc[ai][bj][m][0][1]); w.y = cvt_pk_bf16(acc[ai][bj][m][0][2], acc[ai][bj][m][0][3]);
;                         w.z = cvt_pk_bf16(acc[ai][bj][m][1][0], acc[ai][bj][m][1][1]); w.w = cvt_pk_bf16(acc[ai][bj][m][1][2], acc[ai][bj][m][1][3]);
;                         *(GAS u32x4*)(MG + (size_t)(rowi + m * 16) * D + col0 + bj * HALF) = w; } }
.Lme_fin2:
	v_pk_mul_f32 v[118:119], v[118:119], v[228:229]
	v_pk_mul_f32 v[120:121], v[120:121], v[230:231]
	v_pk_mul_f32 v[114:115], v[114:115], v[232:233]
	v_pk_mul_f32 v[116:117], v[116:117], v[234:235]
	v_ashrrev_i32_e32 v225, 31, v224
	v_lshlrev_b64 v[178:179], 12, v[224:225]
	v_lshl_add_u64 v[170:171], s[48:49], 0, v[178:179]
	s_and_b64 vcc, exec, s[42:43]
	v_lshl_add_u64 v[170:171], v[216:217], 1, v[170:171]
	s_cbranch_vccnz .LBB0_1137
	v_cvt_pk_bf16_f32 v172, v118, v119
	v_cvt_pk_bf16_f32 v173, v120, v121
	v_cvt_pk_bf16_f32 v174, v114, v115
	v_cvt_pk_bf16_f32 v175, v116, v117
	global_store_dwordx4 v[170:171], v[172:175], off
.LBB0_1137:
	s_nop 1
	v_lshlrev_b32_e32 v228, 16, v166
	v_and_b32_e32 v229, 0xffff0000, v166
	v_lshlrev_b32_e32 v230, 16, v167
	v_and_b32_e32 v231, 0xffff0000, v167
	v_lshlrev_b32_e32 v232, 16, v168
	v_and_b32_e32 v233, 0xffff0000, v168
	v_lshlrev_b32_e32 v234, 16, v169
	v_and_b32_e32 v235, 0xffff0000, v169
	v_pk_mul_f32 v[228:229], v[228:229], s[100:101] op_sel_hi:[1,0]
	v_pk_mul_f32 v[230:231], v[230:231], s[100:101] op_sel_hi:[1,0]
	v_pk_mul_f32 v[232:233], v[232:233], s[100:101] op_sel_hi:[1,0]
	v_pk_mul_f32 v[234:235], v[234:235], s[100:101] op_sel_hi:[1,0]
	v_exp_f32_e32 v228, v228
	v_exp_f32_e32 v229, v229
	v_exp_f32_e32 v230, v230
	v_exp_f32_e32 v231, v231
	v_exp_f32_e32 v232, v232
	v_exp_f32_e32 v233, v233
	v_exp_f32_e32 v234, v234
	v_exp_f32_e32 v235, v235
	v_pk_add_f32 v[228:229], v[228:229], s[100:101] op_sel:[0,1]
	v_pk_add_f32 v[230:231], v[230:231], s[100:101] op_sel:[0,1]
	v_pk_add_f32 v[232:233], v[232:233], s[100:101] op_sel:[0,1]
	v_pk_add_f32 v[234:235], v[234:235], s[100:101] op_sel:[0,1]
	v_rcp_f32_e32 v228, v228
	v_rcp_f32_e32 v229, v229
	v_rcp_f32_e32 v230, v230
	v_rcp_f32_e32 v231, v231
	v_rcp_f32_e32 v232, v232
	v_rcp_f32_e32 v233, v233
	v_rcp_f32_e32 v234, v234
	v_rcp_f32_e32 v235, v235
	s_cmp_lg_u64 s[8:9], 0
	s_cbranch_scc1 .Lme_fin3
	v_lshlrev_b32_e32 v236, 16, v162
	v_and_b32_e32 v237, 0xffff0000, v162
	v_lshlrev_b32_e32 v238, 16, v163
	v_and_b32_e32 v239, 0xffff0000, v163
	v_lshlrev_b32_e32 v240, 16, v164
	v_and_b32_e32 v241, 0xffff0000, v164
	v_lshlrev_b32_e32 v242, 16, v165
	v_and_b32_e32 v243, 0xffff0000, v165
	v_pk_mul_f32 v[236:237], v[236:237], s[100:101] op_sel_hi:[1,0]
	v_pk_mul_f32 v[238:239], v[238:239], s[100:101] op_sel_hi:[1,0]
	v_pk_mul_f32 v[240:241], v[240:241], s[100:101] op_sel_hi:[1,0]
	v_pk_mul_f32 v[242:243], v[242:243], s[100:101] op_sel_hi:[1,0]
	v_exp_f32_e32 v236, v236
	v_exp_f32_e32 v237, v237
	v_exp_f32_e32 v238, v238
	v_exp_f32_e32 v239, v239
	v_exp_f32_e32 v240, v240
	v_exp_f32_e32 v241, v241
	v_exp_f32_e32 v242, v242
	v_exp_f32_e32 v243, v243
	v_pk_add_f32 v[236:237], v[236:237], s[100:101] op_sel:[0,1]
	v_pk_add_f32 v[238:239], v[238:239], s[100:101] op_sel:[0,1]
	v_pk_add_f32 v[240:241], v[240:241], s[100:101] op_sel:[0,1]
	v_pk_add_f32 v[242:243], v[242:243], s[100:101] op_sel:[0,1]
	v_pk_mul_f32 v[228:229], v[228:229], v[236:237]
	v_pk_mul_f32 v[230:231], v[230:231], v[238:239]
	v_pk_mul_f32 v[232:233], v[232:233], v[240:241]
	v_pk_mul_f32 v[234:235], v[234:235], v[242:243]
.Lme_fin3:
	v_pk_mul_f32 v[86:87], v[86:87], v[228:229]
	v_pk_mul_f32 v[88:89], v[88:89], v[230:231]
	v_pk_mul_f32 v[82:83], v[82:83], v[232:233]
	v_pk_mul_f32 v[84:85], v[84:85], v[234:235]
	s_and_b64 vcc, exec, s[42:43]
	s_cbranch_vccnz .LBB0_1139
	v_cvt_pk_bf16_f32 v162, v86, v87
	v_cvt_pk_bf16_f32 v163, v88, v89
	v_cvt_pk_bf16_f32 v164, v82, v83
	v_cvt_pk_bf16_f32 v165, v84, v85
	global_store_dwordx4 v[170:171], v[162:165], off offset:256
.LBB0_1139:
	s_nop 1
	v_lshlrev_b32_e32 v228, 16, v158
	v_and_b32_e32 v229, 0xffff0000, v158
	v_lshlrev_b32_e32 v230, 16, v159
	v_and_b32_e32 v231, 0xffff0000, v159
	v_lshlrev_b32_e32 v232, 16, v160
	v_and_b32_e32 v233, 0xffff0000, v160
	v_lshlrev_b32_e32 v234, 16, v161
	v_and_b32_e32 v235, 0xffff0000, v161
	v_pk_mul_f32 v[228:229], v[228:229], s[100:101] op_sel_hi:[1,0]
	v_pk_mul_f32 v[230:231], v[230:231], s[100:101] op_sel_hi:[1,0]
	v_pk_mul_f32 v[232:233], v[232:233], s[100:101] op_sel_hi:[1,0]
	v_pk_mul_f32 v[234:235], v[234:235], s[100:101] op_sel_hi:[1,0]
	v_exp_f32_e32 v228, v228
	v_exp_f32_e32 v229, v229
	v_exp_f32_e32 v230, v230
	v_exp_f32_e32 v231, v231
	v_exp_f32_e32 v232, v232
	v_exp_f32_e32 v233, v233
	v_exp_f32_e32 v234, v234
	v_exp_f32_e32 v235, v235
	v_pk_add_f32 v[228:229], v[228:229], s[100:101] op_sel:[0,1]
	v_pk_add_f32 v[230:231], v[230:231], s[100:101] op_sel:[0,1]
	v_pk_add_f32 v[232:233], v[232:233], s[100:101] op_sel:[0,1]
	v_pk_add_f32 v[234:235], v[234:235], s[100:101] op_sel:[0,1]
	v_rcp_f32_e32 v228, v228
	v_rcp_f32_e32 v229, v229
	v_rcp_f32_e32 v230, v230
	v_rcp_f32_e32 v231, v231
	v_rcp_f32_e32 v232, v232
	v_rcp_f32_e32 v233, v233
	v_rcp_f32_e32 v234, v234
	v_rcp_f32_e32 v235, v235
	s_cmp_lg_u64 s[8:9], 0
	s_cbranch_scc1 .Lme_fin4
	v_lshlrev_b32_e32 v236, 16, v154
	v_and_b32_e32 v237, 0xffff0000, v154
	v_lshlrev_b32_e32 v238, 16, v155
	v_and_b32_e32 v239, 0xffff0000, v155
	v_lshlrev_b32_e32 v240, 16, v156
	v_and_b32_e32 v241, 0xffff0000, v156
	v_lshlrev_b32_e32 v242, 16, v157
	v_and_b32_e32 v243, 0xffff0000, v157
	v_pk_mul_f32 v[236:237], v[236:237], s[100:101] op_sel_hi:[1,0]
	v_pk_mul_f32 v[238:239], v[238:239], s[100:101] op_sel_hi:[1,0]
	v_pk_mul_f32 v[240:241], v[240:241], s[100:101] op_sel_hi:[1,0]
	v_pk_mul_f32 v[242:243], v[242:243], s[100:101] op_sel_hi:[1,0]
	v_exp_f32_e32 v236, v236
	v_exp_f32_e32 v237, v237
	v_exp_f32_e32 v238, v238
	v_exp_f32_e32 v239, v239
	v_exp_f32_e32 v240, v240
	v_exp_f32_e32 v241, v241
	v_exp_f32_e32 v242, v242
	v_exp_f32_e32 v243, v243
	v_pk_add_f32 v[236:237], v[236:237], s[100:101] op_sel:[0,1]
	v_pk_add_f32 v[238:239], v[238:239], s[100:101] op_sel:[0,1]
	v_pk_add_f32 v[240:241], v[240:241], s[100:101] op_sel:[0,1]
	v_pk_add_f32 v[242:243], v[242:243], s[100:101] op_sel:[0,1]
	v_pk_mul_f32 v[228:229], v[228:229], v[236:237]
	v_pk_mul_f32 v[230:231], v[230:231], v[238:239]
	v_pk_mul_f32 v[232:233], v[232:233], v[240:241]
	v_pk_mul_f32 v[234:235], v[234:235], v[242:243]
; #define GAS __attribute__((address_space(1)))
; __device__ __forceinline__ unsigned cvt_pk_bf16(float lo, float hi) { unsigned r; asm volatile("v_cvt_pk_bf16_f32 %0, %1, %2" : "=v"(r) : "v"(lo), "v"(hi)); return r; }
;     __device__ __forceinline__ void operator()(f32x4 (&acc)[2][2][4][2], const Unit& u, int wr, int wc, int fr, int fq) const {
;     ...
;             for (int m = 0; m < 4; ++m) {
; #pragma unroll
;                 for (int bj = 0; bj < 2; ++bj) {
;                     const unsigned nn[4] = {zn[m][bj].x, zn[m][bj].y, zn[m][bj].z, zn[m][bj].w}, dd[4] = {zd[m][bj].x, zd[m][bj].y, zd[m][bj].z, zd[m][bj].w};
;                     float f[8];
; #pragma unroll
;                     for (int e = 0; e < 4; ++e) {
;                         const float n0 = __builtin_amdgcn_rcpf(1.0f + __expf(-bflo(nn[e]))), n1 = __builtin_amdgcn_rcpf(1.0f + __expf(-bfhi(nn[e])));
;                         const float d0 = fin ? 1.0f : 1.0f + __expf(-bflo(dd[e])), d1 = fin ? 1.0f : 1.0f + __expf(-bfhi(dd[e]));
;                         f[2 * e] = n0 * d0; f[2 * e + 1] = n1 * d1; }
; #pragma unroll
;                     for (int n = 0; n < 2; ++n)
; #pragma unroll
;                         for (int e = 0; e < 4; ++e) acc[ai][bj][m][n][e] *= f[4 * n + e];
;                     if (fin) { u32x4 w; w.x = cvt_pk_bf16(acc[ai][bj][m][0][0], acc[ai][bj][m][0][1]); w.y = cvt_pk_bf16(acc[ai][bj][m][0][2], acc[ai][bj][m][0][3]);
;                         w.z = cvt_pk_bf16(acc[ai][bj][m][1][0], acc[ai][bj][m][1][1]); w.w = cvt_pk_bf16(acc[ai][bj][m][1][2], acc[ai][bj][m][1][3]);
;                         *(GAS u32x4*)(MG + (size_t)(rowi + m * 16) * D + col0 + bj * HALF) = w; } }
.Lme_fin4:
	v_pk_mul_f32 v[110:111], v[110:111], v[228:229]
	v_pk_mul_f32 v[112:113], v[112:113], v[230:231]
	v_pk_mul_f32 v[106:107], v[106:107], v[232:233]
	v_pk_mul_f32 v[108:109], v[108:109], v[234:235]
	v_ashrrev_i32_e32 v223, 31, v222
	v_lshlrev_b64 v[162:163], 12, v[222:223]
	v_lshl_add_u64 v[154:155], s[48:49], 0, v[162:163]
	s_and_b64 vcc, exec, s[42:43]
	v_lshl_add_u64 v[154:155], v[216:217], 1, v[154:155]
	s_cbranch_vccnz .LBB0_1141
	v_cvt_pk_bf16_f32 v156, v110, v111
	v_cvt_pk_bf16_f32 v157, v112, v113
	v_cvt_pk_bf16_f32 v158, v106, v107
	v_cvt_pk_bf16_f32 v159, v108, v109
	global_store_dwordx4 v[154:155], v[156:159], off
.LBB0_1141:
	s_nop 1
	v_lshlrev_b32_e32 v228, 16, v150
	v_and_b32_e32 v229, 0xffff0000, v150
	v_lshlrev_b32_e32 v230, 16, v151
	v_and_b32_e32 v231, 0xffff0000, v151
	v_lshlrev_b32_e32 v232, 16, v152
	v_and_b32_e32 v233, 0xffff0000, v152
	v_lshlrev_b32_e32 v234, 16, v153
	v_and_b32_e32 v235, 0xffff0000, v153
	v_pk_mul_f32 v[228:229], v[228:229], s[100:101] op_sel_hi:[1,0]
	v_pk_mul_f32 v[230:231], v[230:231], s[100:101] op_sel_hi:[1,0]
	v_pk_mul_f32 v[232:233], v[232:233], s[100:101] op_sel_hi:[1,0]
	v_pk_mul_f32 v[234:235], v[234:235], s[100:101] op_sel_hi:[1,0]
	v_exp_f32_e32 v228, v228
	v_exp_f32_e32 v229, v229
	v_exp_f32_e32 v230, v230
	v_exp_f32_e32 v231, v231
	v_exp_f32_e32 v232, v232
	v_exp_f32_e32 v233, v233
	v_exp_f32_e32 v234, v234
	v_exp_f32_e32 v235, v235
	v_pk_add_f32 v[228:229], v[228:229], s[100:101] op_sel:[0,1]
	v_pk_add_f32 v[230:231], v[230:231], s[100:101] op_sel:[0,1]
	v_pk_add_f32 v[232:233], v[232:233], s[100:101] op_sel:[0,1]
	v_pk_add_f32 v[234:235], v[234:235], s[100:101] op_sel:[0,1]
	v_rcp_f32_e32 v228, v228
	v_rcp_f32_e32 v229, v229
	v_rcp_f32_e32 v230, v230
	v_rcp_f32_e32 v231, v231
	v_rcp_f32_e32 v232, v232
	v_rcp_f32_e32 v233, v233
	v_rcp_f32_e32 v234, v234
	v_rcp_f32_e32 v235, v235
	s_cmp_lg_u64 s[8:9], 0
	s_cbranch_scc1 .Lme_fin5
	v_lshlrev_b32_e32 v236, 16, v146
	v_and_b32_e32 v237, 0xffff0000, v146
	v_lshlrev_b32_e32 v238, 16, v147
	v_and_b32_e32 v239, 0xffff0000, v147
	v_lshlrev_b32_e32 v240, 16, v148
	v_and_b32_e32 v241, 0xffff0000, v148
	v_lshlrev_b32_e32 v242, 16, v149
	v_and_b32_e32 v243, 0xffff0000, v149
	v_pk_mul_f32 v[236:237], v[236:237], s[100:101] op_sel_hi:[1,0]
	v_pk_mul_f32 v[238:239], v[238:239], s[100:101] op_sel_hi:[1,0]
	v_pk_mul_f32 v[240:241], v[240:241], s[100:101] op_sel_hi:[1,0]
	v_pk_mul_f32 v[242:243], v[242:243], s[100:101] op_sel_hi:[1,0]
	v_exp_f32_e32 v236, v236
	v_exp_f32_e32 v237, v237
	v_exp_f32_e32 v238, v238
	v_exp_f32_e32 v239, v239
	v_exp_f32_e32 v240, v240
	v_exp_f32_e32 v241, v241
	v_exp_f32_e32 v242, v242
	v_exp_f32_e32 v243, v243
	v_pk_add_f32 v[236:237], v[236:237], s[100:101] op_sel:[0,1]
	v_pk_add_f32 v[238:239], v[238:239], s[100:101] op_sel:[0,1]
	v_pk_add_f32 v[240:241], v[240:241], s[100:101] op_sel:[0,1]
	v_pk_add_f32 v[242:243], v[242:243], s[100:101] op_sel:[0,1]
	v_pk_mul_f32 v[228:229], v[228:229], v[236:237]
	v_pk_mul_f32 v[230:231], v[230:231], v[238:239]
	v_pk_mul_f32 v[232:233], v[232:233], v[240:241]
	v_pk_mul_f32 v[234:235], v[234:235], v[242:243]
.Lme_fin5:
	v_pk_mul_f32 v[78:79], v[78:79], v[228:229]
	v_pk_mul_f32 v[80:81], v[80:81], v[230:231]
	v_pk_mul_f32 v[74:75], v[74:75], v[232:233]
	v_pk_mul_f32 v[76:77], v[76:77], v[234:235]
	s_and_b64 vcc, exec, s[42:43]
	s_cbranch_vccnz .LBB0_1143
	v_cvt_pk_bf16_f32 v146, v78, v79
	v_cvt_pk_bf16_f32 v147, v80, v81
	v_cvt_pk_bf16_f32 v148, v74, v75
	v_cvt_pk_bf16_f32 v149, v76, v77
	global_store_dwordx4 v[154:155], v[146:149], off offset:256
.LBB0_1143:
	s_nop 1
	v_lshlrev_b32_e32 v228, 16, v142
	v_and_b32_e32 v229, 0xffff0000, v142
	v_lshlrev_b32_e32 v230, 16, v143
	v_and_b32_e32 v231, 0xffff0000, v143
	v_lshlrev_b32_e32 v232, 16, v144
	v_and_b32_e32 v233, 0xffff0000, v144
	v_lshlrev_b32_e32 v234, 16, v145
	v_and_b32_e32 v235, 0xffff0000, v145
	v_pk_mul_f32 v[228:229], v[228:229], s[100:101] op_sel_hi:[1,0]
	v_pk_mul_f32 v[230:231], v[230:231], s[100:101] op_sel_hi:[1,0]
	v_pk_mul_f32 v[232:233], v[232:233], s[100:101] op_sel_hi:[1,0]
	v_pk_mul_f32 v[234:235], v[234:235], s[100:101] op_sel_hi:[1,0]
	v_exp_f32_e32 v228, v228
	v_exp_f32_e32 v229, v229
	v_exp_f32_e32 v230, v230
	v_exp_f32_e32 v231, v231
	v_exp_f32_e32 v232, v232
	v_exp_f32_e32 v233, v233
	v_exp_f32_e32 v234, v234
	v_exp_f32_e32 v235, v235
	v_pk_add_f32 v[228:229], v[228:229], s[100:101] op_sel:[0,1]
	v_pk_add_f32 v[230:231], v[230:231], s[100:101] op_sel:[0,1]
	v_pk_add_f32 v[232:233], v[232:233], s[100:101] op_sel:[0,1]
	v_pk_add_f32 v[234:235], v[234:235], s[100:101] op_sel:[0,1]
	v_rcp_f32_e32 v228, v228
	v_rcp_f32_e32 v229, v229
	v_rcp_f32_e32 v230, v230
	v_rcp_f32_e32 v231, v231
	v_rcp_f32_e32 v232, v232
	v_rcp_f32_e32 v233, v233
	v_rcp_f32_e32 v234, v234
	v_rcp_f32_e32 v235, v235
	s_cmp_lg_u64 s[8:9], 0
	s_cbranch_scc1 .Lme_fin6
	v_lshlrev_b32_e32 v236, 16, v138
	v_and_b32_e32 v237, 0xffff0000, v138
	v_lshlrev_b32_e32 v238, 16, v139
	v_and_b32_e32 v239, 0xffff0000, v139
	v_lshlrev_b32_e32 v240, 16, v140
	v_and_b32_e32 v241, 0xffff0000, v140
	v_lshlrev_b32_e32 v242, 16, v141
	v_and_b32_e32 v243, 0xffff0000, v141
	v_pk_mul_f32 v[236:237], v[236:237], s[100:101] op_sel_hi:[1,0]
	v_pk_mul_f32 v[238:239], v[238:239], s[100:101] op_sel_hi:[1,0]
	v_pk_mul_f32 v[240:241], v[240:241], s[100:101] op_sel_hi:[1,0]
	v_pk_mul_f32 v[242:243], v[242:243], s[100:101] op_sel_hi:[1,0]
	v_exp_f32_e32 v236, v236
	v_exp_f32_e32 v237, v237
	v_exp_f32_e32 v238, v238
	v_exp_f32_e32 v239, v239
	v_exp_f32_e32 v240, v240
	v_exp_f32_e32 v241, v241
	v_exp_f32_e32 v242, v242
	v_exp_f32_e32 v243, v243
	v_pk_add_f32 v[236:237], v[236:237], s[100:101] op_sel:[0,1]
	v_pk_add_f32 v[238:239], v[238:239], s[100:101] op_sel:[0,1]
	v_pk_add_f32 v[240:241], v[240:241], s[100:101] op_sel:[0,1]
	v_pk_add_f32 v[242:243], v[242:243], s[100:101] op_sel:[0,1]
	v_pk_mul_f32 v[228:229], v[228:229], v[236:237]
	v_pk_mul_f32 v[230:231], v[230:231], v[238:239]
	v_pk_mul_f32 v[232:233], v[232:233], v[240:241]
	v_pk_mul_f32 v[234:235], v[234:235], v[242:243]
; #define GAS __attribute__((address_space(1)))
; __device__ __forceinline__ unsigned cvt_pk_bf16(float lo, float hi) { unsigned r; asm volatile("v_cvt_pk_bf16_f32 %0, %1, %2" : "=v"(r) : "v"(lo), "v"(hi)); return r; }
;     __device__ __forceinline__ void operator()(f32x4 (&acc)[2][2][4][2], const Unit& u, int wr, int wc, int fr, int fq) const {
;     ...
;         for (int ai = 0; ai < 2; ++ai) {
;             int rowi = row0 + ai * HALF; asm volatile("" : "+v"(rowi));
;             u32x4 zn[4][2], zd[4][2];
; #pragma unroll
;             for (int m = 0; m < 4; ++m)
; #pragma unroll
;                 for (int bj = 0; bj < 2; ++bj) { const GAS bf16_t* zp = Z + (size_t)(rowi + m * 16) * DIN + col0 + bj * HALF; zn[m][bj] = *(const GAS u32x4*)(zp + offn); zd[m][bj] = *(const GAS u32x4*)(zp + offd); }
; #pragma unroll
;             for (int m = 0; m < 4; ++m) {
; #pragma unroll
;                 for (int bj = 0; bj < 2; ++bj) {
;                     const unsigned nn[4] = {zn[m][bj].x, zn[m][bj].y, zn[m][bj].z, zn[m][bj].w}, dd[4] = {zd[m][bj].x, zd[m][bj].y, zd[m][bj].z, zd[m][bj].w};
;                     float f[8];
; #pragma unroll
;                     for (int e = 0; e < 4; ++e) {
;                         const float n0 = __builtin_amdgcn_rcpf(1.0f + __expf(-bflo(nn[e]))), n1 = __builtin_amdgcn_rcpf(1.0f + __expf(-bfhi(nn[e])));
;                         const float d0 = fin ? 1.0f : 1.0f + __expf(-bflo(dd[e])), d1 = fin ? 1.0f : 1.0f + __expf(-bfhi(dd[e]));
;                         f[2 * e] = n0 * d0; f[2 * e + 1] = n1 * d1; }
; #pragma unroll
;                     for (int n = 0; n < 2; ++n)
; #pragma unroll
;                         for (int e = 0; e < 4; ++e) acc[ai][bj][m][n][e] *= f[4 * n + e];
;                     if (fin) { u32x4 w; w.x = cvt_pk_bf16(acc[ai][bj][m][0][0], acc[ai][bj][m][0][1]); w.y = cvt_pk_bf16(acc[ai][bj][m][0][2], acc[ai][bj][m][0][3]);
;                         w.z = cvt_pk_bf16(acc[ai][bj][m][1][0], acc[ai][bj][m][1][1]); w.w = cvt_pk_bf16(acc[ai][bj][m][1][2], acc[ai][bj][m][1][3]);
;                         *(GAS u32x4*)(MG + (size_t)(rowi + m * 16) * D + col0 + bj * HALF) = w; } }
.Lme_fin6:
	v_pk_mul_f32 v[102:103], v[102:103], v[228:229]
	v_pk_mul_f32 v[104:105], v[104:105], v[230:231]
	v_pk_mul_f32 v[98:99], v[98:99], v[232:233]
	v_pk_mul_f32 v[100:101], v[100:101], v[234:235]
	v_ashrrev_i32_e32 v221, 31, v220
	v_lshlrev_b64 v[146:147], 12, v[220:221]
	v_lshl_add_u64 v[138:139], s[48:49], 0, v[146:147]
	s_and_b64 vcc, exec, s[42:43]
	v_lshl_add_u64 v[138:139], v[216:217], 1, v[138:139]
	s_cbranch_vccnz .LBB0_1145
	v_cvt_pk_bf16_f32 v140, v102, v103
	v_cvt_pk_bf16_f32 v141, v104, v105
	v_cvt_pk_bf16_f32 v142, v98, v99
	v_cvt_pk_bf16_f32 v143, v100, v101
	global_store_dwordx4 v[138:139], v[140:143], off
.LBB0_1145:
	s_nop 1
	v_lshlrev_b32_e32 v228, 16, v134
	v_and_b32_e32 v229, 0xffff0000, v134
	v_lshlrev_b32_e32 v230, 16, v135
	v_and_b32_e32 v231, 0xffff0000, v135
	v_lshlrev_b32_e32 v232, 16, v136
	v_and_b32_e32 v233, 0xffff0000, v136
	v_lshlrev_b32_e32 v234, 16, v137
	v_and_b32_e32 v235, 0xffff0000, v137
	v_pk_mul_f32 v[228:229], v[228:229], s[100:101] op_sel_hi:[1,0]
	v_pk_mul_f32 v[230:231], v[230:231], s[100:101] op_sel_hi:[1,0]
	v_pk_mul_f32 v[232:233], v[232:233], s[100:101] op_sel_hi:[1,0]
	v_pk_mul_f32 v[234:235], v[234:235], s[100:101] op_sel_hi:[1,0]
	v_exp_f32_e32 v228, v228
	v_exp_f32_e32 v229, v229
	v_exp_f32_e32 v230, v230
	v_exp_f32_e32 v231, v231
	v_exp_f32_e32 v232, v232
	v_exp_f32_e32 v233, v233
	v_exp_f32_e32 v234, v234
	v_exp_f32_e32 v235, v235
	v_pk_add_f32 v[228:229], v[228:229], s[100:101] op_sel:[0,1]
	v_pk_add_f32 v[230:231], v[230:231], s[100:101] op_sel:[0,1]
	v_pk_add_f32 v[232:233], v[232:233], s[100:101] op_sel:[0,1]
	v_pk_add_f32 v[234:235], v[234:235], s[100:101] op_sel:[0,1]
	v_rcp_f32_e32 v228, v228
	v_rcp_f32_e32 v229, v229
	v_rcp_f32_e32 v230, v230
	v_rcp_f32_e32 v231, v231
	v_rcp_f32_e32 v232, v232
	v_rcp_f32_e32 v233, v233
	v_rcp_f32_e32 v234, v234
	v_rcp_f32_e32 v235, v235
	s_cmp_lg_u64 s[8:9], 0
	s_cbranch_scc1 .Lme_fin7
	v_lshlrev_b32_e32 v236, 16, v130
	v_and_b32_e32 v237, 0xffff0000, v130
	v_lshlrev_b32_e32 v238, 16, v131
	v_and_b32_e32 v239, 0xffff0000, v131
	v_lshlrev_b32_e32 v240, 16, v132
	v_and_b32_e32 v241, 0xffff0000, v132
	v_lshlrev_b32_e32 v242, 16, v133
	v_and_b32_e32 v243, 0xffff0000, v133
	v_pk_mul_f32 v[236:237], v[236:237], s[100:101] op_sel_hi:[1,0]
	v_pk_mul_f32 v[238:239], v[238:239], s[100:101] op_sel_hi:[1,0]
	v_pk_mul_f32 v[240:241], v[240:241], s[100:101] op_sel_hi:[1,0]
	v_pk_mul_f32 v[242:243], v[242:243], s[100:101] op_sel_hi:[1,0]
	v_exp_f32_e32 v236, v236
	v_exp_f32_e32 v237, v237
	v_exp_f32_e32 v238, v238
	v_exp_f32_e32 v239, v239
	v_exp_f32_e32 v240, v240
	v_exp_f32_e32 v241, v241
	v_exp_f32_e32 v242, v242
	v_exp_f32_e32 v243, v243
	v_pk_add_f32 v[236:237], v[236:237], s[100:101] op_sel:[0,1]
	v_pk_add_f32 v[238:239], v[238:239], s[100:101] op_sel:[0,1]
	v_pk_add_f32 v[240:241], v[240:241], s[100:101] op_sel:[0,1]
	v_pk_add_f32 v[242:243], v[242:243], s[100:101] op_sel:[0,1]
	v_pk_mul_f32 v[228:229], v[228:229], v[236:237]
	v_pk_mul_f32 v[230:231], v[230:231], v[238:239]
	v_pk_mul_f32 v[232:233], v[232:233], v[240:241]
	v_pk_mul_f32 v[234:235], v[234:235], v[242:243]
.Lme_fin7:
	v_pk_mul_f32 v[70:71], v[70:71], v[228:229]
	v_pk_mul_f32 v[72:73], v[72:73], v[230:231]
	v_pk_mul_f32 v[66:67], v[66:67], v[232:233]
	v_pk_mul_f32 v[68:69], v[68:69], v[234:235]
	s_and_b64 vcc, exec, s[42:43]
	s_cbranch_vccnz .LBB0_1147
	v_cvt_pk_bf16_f32 v130, v70, v71
	v_cvt_pk_bf16_f32 v131, v72, v73
	v_cvt_pk_bf16_f32 v132, v66, v67
	v_cvt_pk_bf16_f32 v133, v68, v69
	global_store_dwordx4 v[138:139], v[130:133], off offset:256
.LBB0_1147:
	v_add_u32_e32 v226, 0x80, v248
	s_nop 0
	v_mad_i64_i32 v[130:131], s[4:5], v226, s74, v[218:219]
	v_lshl_add_u64 v[132:133], v[130:131], 0, s[10:11]
	v_add_co_u32_e32 v132, vcc, 0x3000, v132
	v_lshl_add_u64 v[130:131], v[130:131], 0, s[24:25]
	s_nop 0
	v_addc_co_u32_e32 v133, vcc, 0, v133, vcc
	global_load_dwordx4 v[190:193], v[132:133], off
	global_load_dwordx4 v[186:189], v[130:131], off
	global_load_dwordx4 v[182:185], v[132:133], off offset:256
	global_load_dwordx4 v[178:181], v[130:131], off offset:256
	v_add_u32_e32 v224, 16, v226
	v_mad_i64_i32 v[130:131], s[4:5], v224, s74, v[218:219]
	v_lshl_add_u64 v[132:133], v[130:131], 0, s[10:11]
	v_add_co_u32_e32 v132, vcc, 0x3000, v132
	v_lshl_add_u64 v[130:131], v[130:131], 0, s[24:25]
	s_nop 0
	v_addc_co_u32_e32 v133, vcc, 0, v133, vcc
	v_add_u32_e32 v222, 32, v226
	global_load_dwordx4 v[174:177], v[132:133], off
	global_load_dwordx4 v[170:173], v[130:131], off
	global_load_dwordx4 v[166:169], v[132:133], off offset:256
	global_load_dwordx4 v[162:165], v[130:131], off offset:256
	v_mad_i64_i32 v[130:131], s[4:5], v222, s74, v[218:219]
	v_lshl_add_u64 v[132:133], v[130:131], 0, s[10:11]
	v_add_co_u32_e32 v132, vcc, 0x3000, v132
	v_lshl_add_u64 v[130:131], v[130:131], 0, s[24:25]
	s_nop 0
	v_addc_co_u32_e32 v133, vcc, 0, v133, vcc
	v_add_u32_e32 v220, 48, v226
	global_load_dwordx4 v[158:161], v[132:133], off
	global_load_dwordx4 v[154:157], v[130:131], off
	global_load_dwordx4 v[150:153], v[132:133], off offset:256
	global_load_dwordx4 v[146:149], v[130:131], off offset:256
	v_mad_i64_i32 v[130:131], s[4:5], v220, s74, v[218:219]
	v_lshl_add_u64 v[132:133], v[130:131], 0, s[10:11]
	v_add_co_u32_e32 v132, vcc, 0x3000, v132
	v_lshl_add_u64 v[130:131], v[130:131], 0, s[24:25]
	s_nop 0
	v_addc_co_u32_e32 v133, vcc, 0, v133, vcc
	global_load_dwordx4 v[142:145], v[132:133], off
	global_load_dwordx4 v[138:141], v[130:131], off
	global_load_dwordx4 v[134:137], v[132:133], off offset:256
	s_nop 0
	global_load_dwordx4 v[130:133], v[130:131], off offset:256
	v_ashrrev_i32_e32 v227, 31, v226
	v_lshlrev_b64 v[218:219], 12, v[226:227]
	s_and_b64 vcc, exec, s[42:43]
	s_waitcnt vmcnt(14)
	v_lshlrev_b32_e32 v228, 16, v190
	v_and_b32_e32 v229, 0xffff0000, v190
	v_lshlrev_b32_e32 v230, 16, v191
	v_and_b32_e32 v231, 0xffff0000, v191
	v_lshlrev_b32_e32 v232, 16, v192
	v_and_b32_e32 v233, 0xffff0000, v192
	v_lshlrev_b32_e32 v234, 16, v193
	v_and_b32_e32 v235, 0xffff0000, v193
	v_pk_mul_f32 v[228:229], v[228:229], s[100:101] op_sel_hi:[1,0]
	v_pk_mul_f32 v[230:231], v[230:231], s[100:101] op_sel_hi:[1,0]
	v_pk_mul_f32 v[232:233], v[232:233], s[100:101] op_sel_hi:[1,0]
	v_pk_mul_f32 v[234:235], v[234:235], s[100:101] op_sel_hi:[1,0]
	v_exp_f32_e32 v228, v228
	v_exp_f32_e32 v229, v229
	v_exp_f32_e32 v230, v230
	v_exp_f32_e32 v231, v231
	v_exp_f32_e32 v232, v232
	v_exp_f32_e32 v233, v233
	v_exp_f32_e32 v234, v234
	v_exp_f32_e32 v235, v235
	v_pk_add_f32 v[228:229], v[228:229], s[100:101] op_sel:[0,1]
	v_pk_add_f32 v[230:231], v[230:231], s[100:101] op_sel:[0,1]
	v_pk_add_f32 v[232:233], v[232:233], s[100:101] op_sel:[0,1]
	v_pk_add_f32 v[234:235], v[234:235], s[100:101] op_sel:[0,1]
	v_rcp_f32_e32 v228, v228
	v_rcp_f32_e32 v229, v229
	v_rcp_f32_e32 v230, v230
	v_rcp_f32_e32 v231, v231
	v_rcp_f32_e32 v232, v232
	v_rcp_f32_e32 v233, v233
	v_rcp_f32_e32 v234, v234
	v_rcp_f32_e32 v235, v235
	s_cmp_lg_u64 s[8:9], 0
	s_cbranch_scc1 .Lme_fin8
; #define GAS __attribute__((address_space(1)))
; __device__ __forceinline__ unsigned cvt_pk_bf16(float lo, float hi) { unsigned r; asm volatile("v_cvt_pk_bf16_f32 %0, %1, %2" : "=v"(r) : "v"(lo), "v"(hi)); return r; }
;     __device__ __forceinline__ void operator()(f32x4 (&acc)[2][2][4][2], const Unit& u, int wr, int wc, int fr, int fq) const {
;     ...
;             for (int m = 0; m < 4; ++m) {
; #pragma unroll
;                 for (int bj = 0; bj < 2; ++bj) {
;                     const unsigned nn[4] = {zn[m][bj].x, zn[m][bj].y, zn[m][bj].z, zn[m][bj].w}, dd[4] = {zd[m][bj].x, zd[m][bj].y, zd[m][bj].z, zd[m][bj].w};
;                     float f[8];
; #pragma unroll
;                     for (int e = 0; e < 4; ++e) {
;                         const float n0 = __builtin_amdgcn_rcpf(1.0f + __expf(-bflo(nn[e]))), n1 = __builtin_amdgcn_rcpf(1.0f + __expf(-bfhi(nn[e])));
;                         const float d0 = fin ? 1.0f : 1.0f + __expf(-bflo(dd[e])), d1 = fin ? 1.0f : 1.0f + __expf(-bfhi(dd[e]));
;                         f[2 * e] = n0 * d0; f[2 * e + 1] = n1 * d1; }
; #pragma unroll
;                     for (int n = 0; n < 2; ++n)
; #pragma unroll
;                         for (int e = 0; e < 4; ++e) acc[ai][bj][m][n][e] *= f[4 * n + e];
;                     if (fin) { u32x4 w; w.x = cvt_pk_bf16(acc[ai][bj][m][0][0], acc[ai][bj][m][0][1]); w.y = cvt_pk_bf16(acc[ai][bj][m][0][2], acc[ai][bj][m][0][3]);
;                         w.z = cvt_pk_bf16(acc[ai][bj][m][1][0], acc[ai][bj][m][1][1]); w.w = cvt_pk_bf16(acc[ai][bj][m][1][2], acc[ai][bj][m][1][3]);
;                         *(GAS u32x4*)(MG + (size_t)(rowi + m * 16) * D + col0 + bj * HALF) = w; } }
	v_lshlrev_b32_e32 v236, 16, v186
	v_and_b32_e32 v237, 0xffff0000, v186
	v_lshlrev_b32_e32 v238, 16, v187
	v_and_b32_e32 v239, 0xffff0000, v187
	v_lshlrev_b32_e32 v240, 16, v188
	v_and_b32_e32 v241, 0xffff0000, v188
	v_lshlrev_b32_e32 v242, 16, v189
	v_and_b32_e32 v243, 0xffff0000, v189
	v_pk_mul_f32 v[236:237], v[236:237], s[100:101] op_sel_hi:[1,0]
	v_pk_mul_f32 v[238:239], v[238:239], s[100:101] op_sel_hi:[1,0]
	v_pk_mul_f32 v[240:241], v[240:241], s[100:101] op_sel_hi:[1,0]
	v_pk_mul_f32 v[242:243], v[242:243], s[100:101] op_sel_hi:[1,0]
	v_exp_f32_e32 v236, v236
	v_exp_f32_e32 v237, v237
	v_exp_f32_e32 v238, v238
	v_exp_f32_e32 v239, v239
	v_exp_f32_e32 v240, v240
	v_exp_f32_e32 v241, v241
	v_exp_f32_e32 v242, v242
	v_exp_f32_e32 v243, v243
	v_pk_add_f32 v[236:237], v[236:237], s[100:101] op_sel:[0,1]
	v_pk_add_f32 v[238:239], v[238:239], s[100:101] op_sel:[0,1]
	v_pk_add_f32 v[240:241], v[240:241], s[100:101] op_sel:[0,1]
	v_pk_add_f32 v[242:243], v[242:243], s[100:101] op_sel:[0,1]
	v_pk_mul_f32 v[228:229], v[228:229], v[236:237]
	v_pk_mul_f32 v[230:231], v[230:231], v[238:239]
	v_pk_mul_f32 v[232:233], v[232:233], v[240:241]
	v_pk_mul_f32 v[234:235], v[234:235], v[242:243]
.Lme_fin8:
	v_pk_mul_f32 v[62:63], v[62:63], v[228:229]
	v_pk_mul_f32 v[64:65], v[64:65], v[230:231]
	v_pk_mul_f32 v[58:59], v[58:59], v[232:233]
	v_pk_mul_f32 v[60:61], v[60:61], v[234:235]
	v_lshl_add_u64 v[186:187], s[48:49], 0, v[218:219]
	v_lshl_add_u64 v[186:187], v[216:217], 1, v[186:187]
	s_cbranch_vccnz .LBB0_1149
	v_cvt_pk_bf16_f32 v188, v62, v63
	v_cvt_pk_bf16_f32 v189, v64, v65
	v_cvt_pk_bf16_f32 v190, v58, v59
	v_cvt_pk_bf16_f32 v191, v60, v61
	global_store_dwordx4 v[186:187], v[188:191], off
.LBB0_1149:
	s_waitcnt vmcnt(13)
	s_nop 0
	s_waitcnt vmcnt(12)
	v_lshlrev_b32_e32 v228, 16, v182
	v_and_b32_e32 v229, 0xffff0000, v182
	v_lshlrev_b32_e32 v230, 16, v183
	v_and_b32_e32 v231, 0xffff0000, v183
	v_lshlrev_b32_e32 v232, 16, v184
	v_and_b32_e32 v233, 0xffff0000, v184
	v_lshlrev_b32_e32 v234, 16, v185
	v_and_b32_e32 v235, 0xffff0000, v185
	v_pk_mul_f32 v[228:229], v[228:229], s[100:101] op_sel_hi:[1,0]
	v_pk_mul_f32 v[230:231], v[230:231], s[100:101] op_sel_hi:[1,0]
	v_pk_mul_f32 v[232:233], v[232:233], s[100:101] op_sel_hi:[1,0]
	v_pk_mul_f32 v[234:235], v[234:235], s[100:101] op_sel_hi:[1,0]
	v_exp_f32_e32 v228, v228
	v_exp_f32_e32 v229, v229
	v_exp_f32_e32 v230, v230
	v_exp_f32_e32 v231, v231
	v_exp_f32_e32 v232, v232
	v_exp_f32_e32 v233, v233
	v_exp_f32_e32 v234, v234
	v_exp_f32_e32 v235, v235
	v_pk_add_f32 v[228:229], v[228:229], s[100:101] op_sel:[0,1]
	v_pk_add_f32 v[230:231], v[230:231], s[100:101] op_sel:[0,1]
	v_pk_add_f32 v[232:233], v[232:233], s[100:101] op_sel:[0,1]
	v_pk_add_f32 v[234:235], v[234:235], s[100:101] op_sel:[0,1]
	v_rcp_f32_e32 v228, v228
	v_rcp_f32_e32 v229, v229
	v_rcp_f32_e32 v230, v230
	v_rcp_f32_e32 v231, v231
	v_rcp_f32_e32 v232, v232
	v_rcp_f32_e32 v233, v233
	v_rcp_f32_e32 v234, v234
	v_rcp_f32_e32 v235, v235
	s_cmp_lg_u64 s[8:9], 0
	s_cbranch_scc1 .Lme_fin9
	v_lshlrev_b32_e32 v236, 16, v178
	v_and_b32_e32 v237, 0xffff0000, v178
	v_lshlrev_b32_e32 v238, 16, v179
	v_and_b32_e32 v239, 0xffff0000, v179
	v_lshlrev_b32_e32 v240, 16, v180
	v_and_b32_e32 v241, 0xffff0000, v180
	v_lshlrev_b32_e32 v242, 16, v181
	v_and_b32_e32 v243, 0xffff0000, v181
	v_pk_mul_f32 v[236:237], v[236:237], s[100:101] op_sel_hi:[1,0]
	v_pk_mul_f32 v[238:239], v[238:239], s[100:101] op_sel_hi:[1,0]
	v_pk_mul_f32 v[240:241], v[240:241], s[100:101] op_sel_hi:[1,0]
	v_pk_mul_f32 v[242:243], v[242:243], s[100:101] op_sel_hi:[1,0]
	v_exp_f32_e32 v236, v236
	v_exp_f32_e32 v237, v237
	v_exp_f32_e32 v238, v238
	v_exp_f32_e32 v239, v239
	v_exp_f32_e32 v240, v240
	v_exp_f32_e32 v241, v241
	v_exp_f32_e32 v242, v242
	v_exp_f32_e32 v243, v243
	v_pk_add_f32 v[236:237], v[236:237], s[100:101] op_sel:[0,1]
	v_pk_add_f32 v[238:239], v[238:239], s[100:101] op_sel:[0,1]
	v_pk_add_f32 v[240:241], v[240:241], s[100:101] op_sel:[0,1]
	v_pk_add_f32 v[242:243], v[242:243], s[100:101] op_sel:[0,1]
	v_pk_mul_f32 v[228:229], v[228:229], v[236:237]
	v_pk_mul_f32 v[230:231], v[230:231], v[238:239]
	v_pk_mul_f32 v[232:233], v[232:233], v[240:241]
	v_pk_mul_f32 v[234:235], v[234:235], v[242:243]
.Lme_fin9:
	v_pk_mul_f32 v[30:31], v[30:31], v[228:229]
	v_pk_mul_f32 v[32:33], v[32:33], v[230:231]
	v_pk_mul_f32 v[26:27], v[26:27], v[232:233]
	v_pk_mul_f32 v[28:29], v[28:29], v[234:235]
	s_and_b64 vcc, exec, s[42:43]
	s_cbranch_vccnz .LBB0_1151
	v_cvt_pk_bf16_f32 v178, v30, v31
	v_cvt_pk_bf16_f32 v179, v32, v33
	v_cvt_pk_bf16_f32 v180, v26, v27
	v_cvt_pk_bf16_f32 v181, v28, v29
	global_store_dwordx4 v[186:187], v[178:181], off offset:256
; #define GAS __attribute__((address_space(1)))
; __device__ __forceinline__ unsigned cvt_pk_bf16(float lo, float hi) { unsigned r; asm volatile("v_cvt_pk_bf16_f32 %0, %1, %2" : "=v"(r) : "v"(lo), "v"(hi)); return r; }
;     __device__ __forceinline__ void operator()(f32x4 (&acc)[2][2][4][2], const Unit& u, int wr, int wc, int fr, int fq) const {
;     ...
;             for (int m = 0; m < 4; ++m) {
; #pragma unroll
;                 for (int bj = 0; bj < 2; ++bj) {
;                     const unsigned nn[4] = {zn[m][bj].x, zn[m][bj].y, zn[m][bj].z, zn[m][bj].w}, dd[4] = {zd[m][bj].x, zd[m][bj].y, zd[m][bj].z, zd[m][bj].w};
;                     float f[8];
; #pragma unroll
;                     for (int e = 0; e < 4; ++e) {
;                         const float n0 = __builtin_amdgcn_rcpf(1.0f + __expf(-bflo(nn[e]))), n1 = __builtin_amdgcn_rcpf(1.0f + __expf(-bfhi(nn[e])));
;                         const float d0 = fin ? 1.0f : 1.0f + __expf(-bflo(dd[e])), d1 = fin ? 1.0f : 1.0f + __expf(-bfhi(dd[e]));
;                         f[2 * e] = n0 * d0; f[2 * e + 1] = n1 * d1; }
; #pragma unroll
;                     for (int n = 0; n < 2; ++n)
; #pragma unroll
;                         for (int e = 0; e < 4; ++e) acc[ai][bj][m][n][e] *= f[4 * n + e];
;                     if (fin) { u32x4 w; w.x = cvt_pk_bf16(acc[ai][bj][m][0][0], acc[ai][bj][m][0][1]); w.y = cvt_pk_bf16(acc[ai][bj][m][0][2], acc[ai][bj][m][0][3]);
;                         w.z = cvt_pk_bf16(acc[ai][bj][m][1][0], acc[ai][bj][m][1][1]); w.w = cvt_pk_bf16(acc[ai][bj][m][1][2], acc[ai][bj][m][1][3]);
;                         *(GAS u32x4*)(MG + (size_t)(rowi + m * 16) * D + col0 + bj * HALF) = w; } }
.LBB0_1151:
	s_waitcnt vmcnt(11)
	s_nop 0
	s_waitcnt vmcnt(10)
	v_lshlrev_b32_e32 v228, 16, v174
	v_and_b32_e32 v229, 0xffff0000, v174
	v_lshlrev_b32_e32 v230, 16, v175
	v_and_b32_e32 v231, 0xffff0000, v175
	v_lshlrev_b32_e32 v232, 16, v176
	v_and_b32_e32 v233, 0xffff0000, v176
	v_lshlrev_b32_e32 v234, 16, v177
	v_and_b32_e32 v235, 0xffff0000, v177
	v_pk_mul_f32 v[228:229], v[228:229], s[100:101] op_sel_hi:[1,0]
	v_pk_mul_f32 v[230:231], v[230:231], s[100:101] op_sel_hi:[1,0]
	v_pk_mul_f32 v[232:233], v[232:233], s[100:101] op_sel_hi:[1,0]
	v_pk_mul_f32 v[234:235], v[234:235], s[100:101] op_sel_hi:[1,0]
	v_exp_f32_e32 v228, v228
	v_exp_f32_e32 v229, v229
	v_exp_f32_e32 v230, v230
	v_exp_f32_e32 v231, v231
	v_exp_f32_e32 v232, v232
	v_exp_f32_e32 v233, v233
	v_exp_f32_e32 v234, v234
	v_exp_f32_e32 v235, v235
	v_pk_add_f32 v[228:229], v[228:229], s[100:101] op_sel:[0,1]
	v_pk_add_f32 v[230:231], v[230:231], s[100:101] op_sel:[0,1]
	v_pk_add_f32 v[232:233], v[232:233], s[100:101] op_sel:[0,1]
	v_pk_add_f32 v[234:235], v[234:235], s[100:101] op_sel:[0,1]
	v_rcp_f32_e32 v228, v228
	v_rcp_f32_e32 v229, v229
	v_rcp_f32_e32 v230, v230
	v_rcp_f32_e32 v231, v231
	v_rcp_f32_e32 v232, v232
	v_rcp_f32_e32 v233, v233
	v_rcp_f32_e32 v234, v234
	v_rcp_f32_e32 v235, v235
	s_cmp_lg_u64 s[8:9], 0
	s_cbranch_scc1 .Lme_fin10
	v_lshlrev_b32_e32 v236, 16, v170
	v_and_b32_e32 v237, 0xffff0000, v170
	v_lshlrev_b32_e32 v238, 16, v171
	v_and_b32_e32 v239, 0xffff0000, v171
	v_lshlrev_b32_e32 v240, 16, v172
	v_and_b32_e32 v241, 0xffff0000, v172
	v_lshlrev_b32_e32 v242, 16, v173
	v_and_b32_e32 v243, 0xffff0000, v173
	v_pk_mul_f32 v[236:237], v[236:237], s[100:101] op_sel_hi:[1,0]
	v_pk_mul_f32 v[238:239], v[238:239], s[100:101] op_sel_hi:[1,0]
	v_pk_mul_f32 v[240:241], v[240:241], s[100:101] op_sel_hi:[1,0]
	v_pk_mul_f32 v[242:243], v[242:243], s[100:101] op_sel_hi:[1,0]
	v_exp_f32_e32 v236, v236
	v_exp_f32_e32 v237, v237
	v_exp_f32_e32 v238, v238
	v_exp_f32_e32 v239, v239
	v_exp_f32_e32 v240, v240
	v_exp_f32_e32 v241, v241
	v_exp_f32_e32 v242, v242
	v_exp_f32_e32 v243, v243
	v_pk_add_f32 v[236:237], v[236:237], s[100:101] op_sel:[0,1]
	v_pk_add_f32 v[238:239], v[238:239], s[100:101] op_sel:[0,1]
	v_pk_add_f32 v[240:241], v[240:241], s[100:101] op_sel:[0,1]
	v_pk_add_f32 v[242:243], v[242:243], s[100:101] op_sel:[0,1]
	v_pk_mul_f32 v[228:229], v[228:229], v[236:237]
	v_pk_mul_f32 v[230:231], v[230:231], v[238:239]
	v_pk_mul_f32 v[232:233], v[232:233], v[240:241]
	v_pk_mul_f32 v[234:235], v[234:235], v[242:243]
.Lme_fin10:
	v_pk_mul_f32 v[54:55], v[54:55], v[228:229]
	v_pk_mul_f32 v[56:57], v[56:57], v[230:231]
	v_pk_mul_f32 v[50:51], v[50:51], v[232:233]
	v_pk_mul_f32 v[52:53], v[52:53], v[234:235]
	v_ashrrev_i32_e32 v225, 31, v224
	v_lshlrev_b64 v[178:179], 12, v[224:225]
	v_lshl_add_u64 v[170:171], s[48:49], 0, v[178:179]
	s_and_b64 vcc, exec, s[42:43]
	v_lshl_add_u64 v[170:171], v[216:217], 1, v[170:171]
	s_cbranch_vccnz .LBB0_1153
	v_cvt_pk_bf16_f32 v172, v54, v55
	v_cvt_pk_bf16_f32 v173, v56, v57
	v_cvt_pk_bf16_f32 v174, v50, v51
	v_cvt_pk_bf16_f32 v175, v52, v53
	global_store_dwordx4 v[170:171], v[172:175], off
.LBB0_1153:
	s_waitcnt vmcnt(9)
	s_nop 0
	s_waitcnt vmcnt(8)
	v_lshlrev_b32_e32 v228, 16, v166
	v_and_b32_e32 v229, 0xffff0000, v166
	v_lshlrev_b32_e32 v230, 16, v167
	v_and_b32_e32 v231, 0xffff0000, v167
	v_lshlrev_b32_e32 v232, 16, v168
	v_and_b32_e32 v233, 0xffff0000, v168
	v_lshlrev_b32_e32 v234, 16, v169
	v_and_b32_e32 v235, 0xffff0000, v169
	v_pk_mul_f32 v[228:229], v[228:229], s[100:101] op_sel_hi:[1,0]
	v_pk_mul_f32 v[230:231], v[230:231], s[100:101] op_sel_hi:[1,0]
	v_pk_mul_f32 v[232:233], v[232:233], s[100:101] op_sel_hi:[1,0]
	v_pk_mul_f32 v[234:235], v[234:235], s[100:101] op_sel_hi:[1,0]
	v_exp_f32_e32 v228, v228
	v_exp_f32_e32 v229, v229
	v_exp_f32_e32 v230, v230
	v_exp_f32_e32 v231, v231
	v_exp_f32_e32 v232, v232
	v_exp_f32_e32 v233, v233
	v_exp_f32_e32 v234, v234
	v_exp_f32_e32 v235, v235
	v_pk_add_f32 v[228:229], v[228:229], s[100:101] op_sel:[0,1]
	v_pk_add_f32 v[230:231], v[230:231], s[100:101] op_sel:[0,1]
	v_pk_add_f32 v[232:233], v[232:233], s[100:101] op_sel:[0,1]
	v_pk_add_f32 v[234:235], v[234:235], s[100:101] op_sel:[0,1]
	v_rcp_f32_e32 v228, v228
	v_rcp_f32_e32 v229, v229
	v_rcp_f32_e32 v230, v230
	v_rcp_f32_e32 v231, v231
	v_rcp_f32_e32 v232, v232
	v_rcp_f32_e32 v233, v233
	v_rcp_f32_e32 v234, v234
	v_rcp_f32_e32 v235, v235
	s_cmp_lg_u64 s[8:9], 0
	s_cbranch_scc1 .Lme_fin11
	v_lshlrev_b32_e32 v236, 16, v162
	v_and_b32_e32 v237, 0xffff0000, v162
	v_lshlrev_b32_e32 v238, 16, v163
	v_and_b32_e32 v239, 0xffff0000, v163
	v_lshlrev_b32_e32 v240, 16, v164
	v_and_b32_e32 v241, 0xffff0000, v164
	v_lshlrev_b32_e32 v242, 16, v165
	v_and_b32_e32 v243, 0xffff0000, v165
	v_pk_mul_f32 v[236:237], v[236:237], s[100:101] op_sel_hi:[1,0]
	v_pk_mul_f32 v[238:239], v[238:239], s[100:101] op_sel_hi:[1,0]
	v_pk_mul_f32 v[240:241], v[240:241], s[100:101] op_sel_hi:[1,0]
	v_pk_mul_f32 v[242:243], v[242:243], s[100:101] op_sel_hi:[1,0]
	v_exp_f32_e32 v236, v236
	v_exp_f32_e32 v237, v237
	v_exp_f32_e32 v238, v238
	v_exp_f32_e32 v239, v239
	v_exp_f32_e32 v240, v240
	v_exp_f32_e32 v241, v241
	v_exp_f32_e32 v242, v242
	v_exp_f32_e32 v243, v243
	v_pk_add_f32 v[236:237], v[236:237], s[100:101] op_sel:[0,1]
	v_pk_add_f32 v[238:239], v[238:239], s[100:101] op_sel:[0,1]
	v_pk_add_f32 v[240:241], v[240:241], s[100:101] op_sel:[0,1]
	v_pk_add_f32 v[242:243], v[242:243], s[100:101] op_sel:[0,1]
	v_pk_mul_f32 v[228:229], v[228:229], v[236:237]
	v_pk_mul_f32 v[230:231], v[230:231], v[238:239]
	v_pk_mul_f32 v[232:233], v[232:233], v[240:241]
	v_pk_mul_f32 v[234:235], v[234:235], v[242:243]
; #define GAS __attribute__((address_space(1)))
; __device__ __forceinline__ unsigned cvt_pk_bf16(float lo, float hi) { unsigned r; asm volatile("v_cvt_pk_bf16_f32 %0, %1, %2" : "=v"(r) : "v"(lo), "v"(hi)); return r; }
;     __device__ __forceinline__ void operator()(f32x4 (&acc)[2][2][4][2], const Unit& u, int wr, int wc, int fr, int fq) const {
;     ...
;             for (int m = 0; m < 4; ++m) {
; #pragma unroll
;                 for (int bj = 0; bj < 2; ++bj) {
;                     const unsigned nn[4] = {zn[m][bj].x, zn[m][bj].y, zn[m][bj].z, zn[m][bj].w}, dd[4] = {zd[m][bj].x, zd[m][bj].y, zd[m][bj].z, zd[m][bj].w};
;                     float f[8];
; #pragma unroll
;                     for (int e = 0; e < 4; ++e) {
;                         const float n0 = __builtin_amdgcn_rcpf(1.0f + __expf(-bflo(nn[e]))), n1 = __builtin_amdgcn_rcpf(1.0f + __expf(-bfhi(nn[e])));
;                         const float d0 = fin ? 1.0f : 1.0f + __expf(-bflo(dd[e])), d1 = fin ? 1.0f : 1.0f + __expf(-bfhi(dd[e]));
;                         f[2 * e] = n0 * d0; f[2 * e + 1] = n1 * d1; }
; #pragma unroll
;                     for (int n = 0; n < 2; ++n)
; #pragma unroll
;                         for (int e = 0; e < 4; ++e) acc[ai][bj][m][n][e] *= f[4 * n + e];
;                     if (fin) { u32x4 w; w.x = cvt_pk_bf16(acc[ai][bj][m][0][0], acc[ai][bj][m][0][1]); w.y = cvt_pk_bf16(acc[ai][bj][m][0][2], acc[ai][bj][m][0][3]);
;                         w.z = cvt_pk_bf16(acc[ai][bj][m][1][0], acc[ai][bj][m][1][1]); w.w = cvt_pk_bf16(acc[ai][bj][m][1][2], acc[ai][bj][m][1][3]);
;                         *(GAS u32x4*)(MG + (size_t)(rowi + m * 16) * D + col0 + bj * HALF) = w; } }
.Lme_fin11:
	v_pk_mul_f32 v[22:23], v[22:23], v[228:229]
	v_pk_mul_f32 v[24:25], v[24:25], v[230:231]
	v_pk_mul_f32 v[18:19], v[18:19], v[232:233]
	v_pk_mul_f32 v[20:21], v[20:21], v[234:235]
	s_and_b64 vcc, exec, s[42:43]
	s_cbranch_vccnz .LBB0_1155
	v_cvt_pk_bf16_f32 v162, v22, v23
	v_cvt_pk_bf16_f32 v163, v24, v25
	v_cvt_pk_bf16_f32 v164, v18, v19
	v_cvt_pk_bf16_f32 v165, v20, v21
	global_store_dwordx4 v[170:171], v[162:165], off offset:256
.LBB0_1155:
	s_waitcnt vmcnt(7)
	s_nop 0
	s_waitcnt vmcnt(6)
	v_lshlrev_b32_e32 v228, 16, v158
	v_and_b32_e32 v229, 0xffff0000, v158
	v_lshlrev_b32_e32 v230, 16, v159
	v_and_b32_e32 v231, 0xffff0000, v159
	v_lshlrev_b32_e32 v232, 16, v160
	v_and_b32_e32 v233, 0xffff0000, v160
	v_lshlrev_b32_e32 v234, 16, v161
	v_and_b32_e32 v235, 0xffff0000, v161
	v_pk_mul_f32 v[228:229], v[228:229], s[100:101] op_sel_hi:[1,0]
	v_pk_mul_f32 v[230:231], v[230:231], s[100:101] op_sel_hi:[1,0]
	v_pk_mul_f32 v[232:233], v[232:233], s[100:101] op_sel_hi:[1,0]
	v_pk_mul_f32 v[234:235], v[234:235], s[100:101] op_sel_hi:[1,0]
	v_exp_f32_e32 v228, v228
	v_exp_f32_e32 v229, v229
	v_exp_f32_e32 v230, v230
	v_exp_f32_e32 v231, v231
	v_exp_f32_e32 v232, v232
	v_exp_f32_e32 v233, v233
	v_exp_f32_e32 v234, v234
	v_exp_f32_e32 v235, v235
	v_pk_add_f32 v[228:229], v[228:229], s[100:101] op_sel:[0,1]
	v_pk_add_f32 v[230:231], v[230:231], s[100:101] op_sel:[0,1]
	v_pk_add_f32 v[232:233], v[232:233], s[100:101] op_sel:[0,1]
	v_pk_add_f32 v[234:235], v[234:235], s[100:101] op_sel:[0,1]
	v_rcp_f32_e32 v228, v228
	v_rcp_f32_e32 v229, v229
	v_rcp_f32_e32 v230, v230
	v_rcp_f32_e32 v231, v231
	v_rcp_f32_e32 v232, v232
	v_rcp_f32_e32 v233, v233
	v_rcp_f32_e32 v234, v234
	v_rcp_f32_e32 v235, v235
	s_cmp_lg_u64 s[8:9], 0
	s_cbranch_scc1 .Lme_fin12
	v_lshlrev_b32_e32 v236, 16, v154
	v_and_b32_e32 v237, 0xffff0000, v154
	v_lshlrev_b32_e32 v238, 16, v155
	v_and_b32_e32 v239, 0xffff0000, v155
	v_lshlrev_b32_e32 v240, 16, v156
	v_and_b32_e32 v241, 0xffff0000, v156
	v_lshlrev_b32_e32 v242, 16, v157
	v_and_b32_e32 v243, 0xffff0000, v157
	v_pk_mul_f32 v[236:237], v[236:237], s[100:101] op_sel_hi:[1,0]
	v_pk_mul_f32 v[238:239], v[238:239], s[100:101] op_sel_hi:[1,0]
	v_pk_mul_f32 v[240:241], v[240:241], s[100:101] op_sel_hi:[1,0]
	v_pk_mul_f32 v[242:243], v[242:243], s[100:101] op_sel_hi:[1,0]
	v_exp_f32_e32 v236, v236
	v_exp_f32_e32 v237, v237
	v_exp_f32_e32 v238, v238
	v_exp_f32_e32 v239, v239
	v_exp_f32_e32 v240, v240
	v_exp_f32_e32 v241, v241
	v_exp_f32_e32 v242, v242
	v_exp_f32_e32 v243, v243
	v_pk_add_f32 v[236:237], v[236:237], s[100:101] op_sel:[0,1]
	v_pk_add_f32 v[238:239], v[238:239], s[100:101] op_sel:[0,1]
	v_pk_add_f32 v[240:241], v[240:241], s[100:101] op_sel:[0,1]
	v_pk_add_f32 v[242:243], v[242:243], s[100:101] op_sel:[0,1]
	v_pk_mul_f32 v[228:229], v[228:229], v[236:237]
	v_pk_mul_f32 v[230:231], v[230:231], v[238:239]
	v_pk_mul_f32 v[232:233], v[232:233], v[240:241]
	v_pk_mul_f32 v[234:235], v[234:235], v[242:243]
.Lme_fin12:
	v_pk_mul_f32 v[46:47], v[46:47], v[228:229]
	v_pk_mul_f32 v[48:49], v[48:49], v[230:231]
	v_pk_mul_f32 v[42:43], v[42:43], v[232:233]
	v_pk_mul_f32 v[44:45], v[44:45], v[234:235]
	v_ashrrev_i32_e32 v223, 31, v222
	v_lshlrev_b64 v[162:163], 12, v[222:223]
	v_lshl_add_u64 v[154:155], s[48:49], 0, v[162:163]
	s_and_b64 vcc, exec, s[42:43]
	v_lshl_add_u64 v[154:155], v[216:217], 1, v[154:155]
	s_cbranch_vccnz .LBB0_1157
	v_cvt_pk_bf16_f32 v156, v46, v47
	v_cvt_pk_bf16_f32 v157, v48, v49
	v_cvt_pk_bf16_f32 v158, v42, v43
	v_cvt_pk_bf16_f32 v159, v44, v45
	global_store_dwordx4 v[154:155], v[156:159], off
.LBB0_1157:
	s_waitcnt vmcnt(5)
	s_nop 0
	s_waitcnt vmcnt(4)
	v_lshlrev_b32_e32 v228, 16, v150
	v_and_b32_e32 v229, 0xffff0000, v150
	v_lshlrev_b32_e32 v230, 16, v151
	v_and_b32_e32 v231, 0xffff0000, v151
	v_lshlrev_b32_e32 v232, 16, v152
	v_and_b32_e32 v233, 0xffff0000, v152
	v_lshlrev_b32_e32 v234, 16, v153
	v_and_b32_e32 v235, 0xffff0000, v153
	v_pk_mul_f32 v[228:229], v[228:229], s[100:101] op_sel_hi:[1,0]
	v_pk_mul_f32 v[230:231], v[230:231], s[100:101] op_sel_hi:[1,0]
	v_pk_mul_f32 v[232:233], v[232:233], s[100:101] op_sel_hi:[1,0]
	v_pk_mul_f32 v[234:235], v[234:235], s[100:101] op_sel_hi:[1,0]
	v_exp_f32_e32 v228, v228
	v_exp_f32_e32 v229, v229
	v_exp_f32_e32 v230, v230
	v_exp_f32_e32 v231, v231
	v_exp_f32_e32 v232, v232
	v_exp_f32_e32 v233, v233
	v_exp_f32_e32 v234, v234
	v_exp_f32_e32 v235, v235
	v_pk_add_f32 v[228:229], v[228:229], s[100:101] op_sel:[0,1]
	v_pk_add_f32 v[230:231], v[230:231], s[100:101] op_sel:[0,1]
	v_pk_add_f32 v[232:233], v[232:233], s[100:101] op_sel:[0,1]
	v_pk_add_f32 v[234:235], v[234:235], s[100:101] op_sel:[0,1]
	v_rcp_f32_e32 v228, v228
	v_rcp_f32_e32 v229, v229
	v_rcp_f32_e32 v230, v230
	v_rcp_f32_e32 v231, v231
	v_rcp_f32_e32 v232, v232
	v_rcp_f32_e32 v233, v233
	v_rcp_f32_e32 v234, v234
	v_rcp_f32_e32 v235, v235
	s_cmp_lg_u64 s[8:9], 0
	s_cbranch_scc1 .Lme_fin13
	v_lshlrev_b32_e32 v236, 16, v146
	v_and_b32_e32 v237, 0xffff0000, v146
	v_lshlrev_b32_e32 v238, 16, v147
	v_and_b32_e32 v239, 0xffff0000, v147
	v_lshlrev_b32_e32 v240, 16, v148
	v_and_b32_e32 v241, 0xffff0000, v148
	v_lshlrev_b32_e32 v242, 16, v149
	v_and_b32_e32 v243, 0xffff0000, v149
	v_pk_mul_f32 v[236:237], v[236:237], s[100:101] op_sel_hi:[1,0]
	v_pk_mul_f32 v[238:239], v[238:239], s[100:101] op_sel_hi:[1,0]
	v_pk_mul_f32 v[240:241], v[240:241], s[100:101] op_sel_hi:[1,0]
	v_pk_mul_f32 v[242:243], v[242:243], s[100:101] op_sel_hi:[1,0]
	v_exp_f32_e32 v236, v236
	v_exp_f32_e32 v237, v237
	v_exp_f32_e32 v238, v238
	v_exp_f32_e32 v239, v239
	v_exp_f32_e32 v240, v240
	v_exp_f32_e32 v241, v241
	v_exp_f32_e32 v242, v242
	v_exp_f32_e32 v243, v243
	v_pk_add_f32 v[236:237], v[236:237], s[100:101] op_sel:[0,1]
	v_pk_add_f32 v[238:239], v[238:239], s[100:101] op_sel:[0,1]
	v_pk_add_f32 v[240:241], v[240:241], s[100:101] op_sel:[0,1]
	v_pk_add_f32 v[242:243], v[242:243], s[100:101] op_sel:[0,1]
	v_pk_mul_f32 v[228:229], v[228:229], v[236:237]
	v_pk_mul_f32 v[230:231], v[230:231], v[238:239]
	v_pk_mul_f32 v[232:233], v[232:233], v[240:241]
	v_pk_mul_f32 v[234:235], v[234:235], v[242:243]
; #define GAS __attribute__((address_space(1)))
; __device__ __forceinline__ unsigned cvt_pk_bf16(float lo, float hi) { unsigned r; asm volatile("v_cvt_pk_bf16_f32 %0, %1, %2" : "=v"(r) : "v"(lo), "v"(hi)); return r; }
;     __device__ __forceinline__ void operator()(f32x4 (&acc)[2][2][4][2], const Unit& u, int wr, int wc, int fr, int fq) const {
;     ...
;             for (int m = 0; m < 4; ++m) {
; #pragma unroll
;                 for (int bj = 0; bj < 2; ++bj) {
;                     const unsigned nn[4] = {zn[m][bj].x, zn[m][bj].y, zn[m][bj].z, zn[m][bj].w}, dd[4] = {zd[m][bj].x, zd[m][bj].y, zd[m][bj].z, zd[m][bj].w};
;                     float f[8];
; #pragma unroll
;                     for (int e = 0; e < 4; ++e) {
;                         const float n0 = __builtin_amdgcn_rcpf(1.0f + __expf(-bflo(nn[e]))), n1 = __builtin_amdgcn_rcpf(1.0f + __expf(-bfhi(nn[e])));
;                         const float d0 = fin ? 1.0f : 1.0f + __expf(-bflo(dd[e])), d1 = fin ? 1.0f : 1.0f + __expf(-bfhi(dd[e]));
;                         f[2 * e] = n0 * d0; f[2 * e + 1] = n1 * d1; }
; #pragma unroll
;                     for (int n = 0; n < 2; ++n)
; #pragma unroll
;                         for (int e = 0; e < 4; ++e) acc[ai][bj][m][n][e] *= f[4 * n + e];
;                     if (fin) { u32x4 w; w.x = cvt_pk_bf16(acc[ai][bj][m][0][0], acc[ai][bj][m][0][1]); w.y = cvt_pk_bf16(acc[ai][bj][m][0][2], acc[ai][bj][m][0][3]);
;                         w.z = cvt_pk_bf16(acc[ai][bj][m][1][0], acc[ai][bj][m][1][1]); w.w = cvt_pk_bf16(acc[ai][bj][m][1][2], acc[ai][bj][m][1][3]);
;                         *(GAS u32x4*)(MG + (size_t)(rowi + m * 16) * D + col0 + bj * HALF) = w; } }
.Lme_fin13:
	v_pk_mul_f32 v[14:15], v[14:15], v[228:229]
	v_pk_mul_f32 v[16:17], v[16:17], v[230:231]
	v_pk_mul_f32 v[10:11], v[10:11], v[232:233]
	v_pk_mul_f32 v[12:13], v[12:13], v[234:235]
	s_and_b64 vcc, exec, s[42:43]
	s_cbranch_vccnz .LBB0_1159
	v_cvt_pk_bf16_f32 v146, v14, v15
	v_cvt_pk_bf16_f32 v147, v16, v17
	v_cvt_pk_bf16_f32 v148, v10, v11
	v_cvt_pk_bf16_f32 v149, v12, v13
	global_store_dwordx4 v[154:155], v[146:149], off offset:256
.LBB0_1159:
	s_waitcnt vmcnt(3)
	s_nop 0
	s_waitcnt vmcnt(2)
	v_lshlrev_b32_e32 v228, 16, v142
	v_and_b32_e32 v229, 0xffff0000, v142
	v_lshlrev_b32_e32 v230, 16, v143
	v_and_b32_e32 v231, 0xffff0000, v143
	v_lshlrev_b32_e32 v232, 16, v144
	v_and_b32_e32 v233, 0xffff0000, v144
	v_lshlrev_b32_e32 v234, 16, v145
	v_and_b32_e32 v235, 0xffff0000, v145
	v_pk_mul_f32 v[228:229], v[228:229], s[100:101] op_sel_hi:[1,0]
	v_pk_mul_f32 v[230:231], v[230:231], s[100:101] op_sel_hi:[1,0]
	v_pk_mul_f32 v[232:233], v[232:233], s[100:101] op_sel_hi:[1,0]
	v_pk_mul_f32 v[234:235], v[234:235], s[100:101] op_sel_hi:[1,0]
	v_exp_f32_e32 v228, v228
	v_exp_f32_e32 v229, v229
	v_exp_f32_e32 v230, v230
	v_exp_f32_e32 v231, v231
	v_exp_f32_e32 v232, v232
	v_exp_f32_e32 v233, v233
	v_exp_f32_e32 v234, v234
	v_exp_f32_e32 v235, v235
	v_pk_add_f32 v[228:229], v[228:229], s[100:101] op_sel:[0,1]
	v_pk_add_f32 v[230:231], v[230:231], s[100:101] op_sel:[0,1]
	v_pk_add_f32 v[232:233], v[232:233], s[100:101] op_sel:[0,1]
	v_pk_add_f32 v[234:235], v[234:235], s[100:101] op_sel:[0,1]
	v_rcp_f32_e32 v228, v228
	v_rcp_f32_e32 v229, v229
	v_rcp_f32_e32 v230, v230
	v_rcp_f32_e32 v231, v231
	v_rcp_f32_e32 v232, v232
	v_rcp_f32_e32 v233, v233
	v_rcp_f32_e32 v234, v234
	v_rcp_f32_e32 v235, v235
	s_cmp_lg_u64 s[8:9], 0
	s_cbranch_scc1 .Lme_fin14
	v_lshlrev_b32_e32 v236, 16, v138
	v_and_b32_e32 v237, 0xffff0000, v138
	v_lshlrev_b32_e32 v238, 16, v139
	v_and_b32_e32 v239, 0xffff0000, v139
	v_lshlrev_b32_e32 v240, 16, v140
	v_and_b32_e32 v241, 0xffff0000, v140
	v_lshlrev_b32_e32 v242, 16, v141
	v_and_b32_e32 v243, 0xffff0000, v141
	v_pk_mul_f32 v[236:237], v[236:237], s[100:101] op_sel_hi:[1,0]
	v_pk_mul_f32 v[238:239], v[238:239], s[100:101] op_sel_hi:[1,0]
	v_pk_mul_f32 v[240:241], v[240:241], s[100:101] op_sel_hi:[1,0]
	v_pk_mul_f32 v[242:243], v[242:243], s[100:101] op_sel_hi:[1,0]
	v_exp_f32_e32 v236, v236
	v_exp_f32_e32 v237, v237
	v_exp_f32_e32 v238, v238
	v_exp_f32_e32 v239, v239
	v_exp_f32_e32 v240, v240
	v_exp_f32_e32 v241, v241
	v_exp_f32_e32 v242, v242
	v_exp_f32_e32 v243, v243
	v_pk_add_f32 v[236:237], v[236:237], s[100:101] op_sel:[0,1]
	v_pk_add_f32 v[238:239], v[238:239], s[100:101] op_sel:[0,1]
	v_pk_add_f32 v[240:241], v[240:241], s[100:101] op_sel:[0,1]
	v_pk_add_f32 v[242:243], v[242:243], s[100:101] op_sel:[0,1]
	v_pk_mul_f32 v[228:229], v[228:229], v[236:237]
	v_pk_mul_f32 v[230:231], v[230:231], v[238:239]
	v_pk_mul_f32 v[232:233], v[232:233], v[240:241]
	v_pk_mul_f32 v[234:235], v[234:235], v[242:243]
.Lme_fin14:
	v_pk_mul_f32 v[38:39], v[38:39], v[228:229]
	v_pk_mul_f32 v[40:41], v[40:41], v[230:231]
	v_pk_mul_f32 v[34:35], v[34:35], v[232:233]
	v_pk_mul_f32 v[36:37], v[36:37], v[234:235]
	v_ashrrev_i32_e32 v221, 31, v220
	v_lshlrev_b64 v[146:147], 12, v[220:221]
	v_lshl_add_u64 v[138:139], s[48:49], 0, v[146:147]
	s_and_b64 vcc, exec, s[42:43]
	v_lshl_add_u64 v[138:139], v[216:217], 1, v[138:139]
	s_cbranch_vccnz .LBB0_1161
	v_cvt_pk_bf16_f32 v140, v38, v39
	v_cvt_pk_bf16_f32 v141, v40, v41
	v_cvt_pk_bf16_f32 v142, v34, v35
	v_cvt_pk_bf16_f32 v143, v36, v37
	global_store_dwordx4 v[138:139], v[140:143], off
.LBB0_1161:
	s_waitcnt vmcnt(1)
	s_nop 0
	s_waitcnt vmcnt(0)
	v_lshlrev_b32_e32 v228, 16, v134
	v_and_b32_e32 v229, 0xffff0000, v134
	v_lshlrev_b32_e32 v230, 16, v135
	v_and_b32_e32 v231, 0xffff0000, v135
	v_lshlrev_b32_e32 v232, 16, v136
	v_and_b32_e32 v233, 0xffff0000, v136
	v_lshlrev_b32_e32 v234, 16, v137
	v_and_b32_e32 v235, 0xffff0000, v137
	v_pk_mul_f32 v[228:229], v[228:229], s[100:101] op_sel_hi:[1,0]
	v_pk_mul_f32 v[230:231], v[230:231], s[100:101] op_sel_hi:[1,0]
	v_pk_mul_f32 v[232:233], v[232:233], s[100:101] op_sel_hi:[1,0]
	v_pk_mul_f32 v[234:235], v[234:235], s[100:101] op_sel_hi:[1,0]
	v_exp_f32_e32 v228, v228
	v_exp_f32_e32 v229, v229
	v_exp_f32_e32 v230, v230
	v_exp_f32_e32 v231, v231
	v_exp_f32_e32 v232, v232
	v_exp_f32_e32 v233, v233
	v_exp_f32_e32 v234, v234
	v_exp_f32_e32 v235, v235
	v_pk_add_f32 v[228:229], v[228:229], s[100:101] op_sel:[0,1]
	v_pk_add_f32 v[230:231], v[230:231], s[100:101] op_sel:[0,1]
	v_pk_add_f32 v[232:233], v[232:233], s[100:101] op_sel:[0,1]
	v_pk_add_f32 v[234:235], v[234:235], s[100:101] op_sel:[0,1]
	v_rcp_f32_e32 v228, v228
	v_rcp_f32_e32 v229, v229
	v_rcp_f32_e32 v230, v230
	v_rcp_f32_e32 v231, v231
	v_rcp_f32_e32 v232, v232
	v_rcp_f32_e32 v233, v233
	v_rcp_f32_e32 v234, v234
	v_rcp_f32_e32 v235, v235
	s_cmp_lg_u64 s[8:9], 0
	s_cbranch_scc1 .Lme_fin15
	v_lshlrev_b32_e32 v236, 16, v130
	v_and_b32_e32 v237, 0xffff0000, v130
	v_lshlrev_b32_e32 v238, 16, v131
	v_and_b32_e32 v239, 0xffff0000, v131
	v_lshlrev_b32_e32 v240, 16, v132
	v_and_b32_e32 v241, 0xffff0000, v132
	v_lshlrev_b32_e32 v242, 16, v133
	v_and_b32_e32 v243, 0xffff0000, v133
	v_pk_mul_f32 v[236:237], v[236:237], s[100:101] op_sel_hi:[1,0]
	v_pk_mul_f32 v[238:239], v[238:239], s[100:101] op_sel_hi:[1,0]
	v_pk_mul_f32 v[240:241], v[240:241], s[100:101] op_sel_hi:[1,0]
	v_pk_mul_f32 v[242:243], v[242:243], s[100:101] op_sel_hi:[1,0]
	v_exp_f32_e32 v236, v236
	v_exp_f32_e32 v237, v237
	v_exp_f32_e32 v238, v238
	v_exp_f32_e32 v239, v239
	v_exp_f32_e32 v240, v240
	v_exp_f32_e32 v241, v241
	v_exp_f32_e32 v242, v242
	v_exp_f32_e32 v243, v243
	v_pk_add_f32 v[236:237], v[236:237], s[100:101] op_sel:[0,1]
	v_pk_add_f32 v[238:239], v[238:239], s[100:101] op_sel:[0,1]
	v_pk_add_f32 v[240:241], v[240:241], s[100:101] op_sel:[0,1]
	v_pk_add_f32 v[242:243], v[242:243], s[100:101] op_sel:[0,1]
	v_pk_mul_f32 v[228:229], v[228:229], v[236:237]
	v_pk_mul_f32 v[230:231], v[230:231], v[238:239]
	v_pk_mul_f32 v[232:233], v[232:233], v[240:241]
	v_pk_mul_f32 v[234:235], v[234:235], v[242:243]
.Lme_fin15:
	v_pk_mul_f32 v[6:7], v[6:7], v[228:229]
	v_pk_mul_f32 v[8:9], v[8:9], v[230:231]
	v_pk_mul_f32 v[2:3], v[2:3], v[232:233]
	v_pk_mul_f32 v[4:5], v[4:5], v[234:235]
	s_and_b64 vcc, exec, s[42:43]
	s_cbranch_vccnz .LBB0_1163
	v_cvt_pk_bf16_f32 v130, v6, v7
	v_cvt_pk_bf16_f32 v131, v8, v9
	v_cvt_pk_bf16_f32 v132, v2, v3
	v_cvt_pk_bf16_f32 v133, v4, v5
	global_store_dwordx4 v[138:139], v[130:133], off offset:256

; #define PG8_WAIT_V(n) asm volatile("s_waitcnt vmcnt(" #n ")" ::: "memory")
; #define PG8_BAR __builtin_amdgcn_s_barrier()
; template <class Epi, class Sched, bool ALIGN_EPI, bool SP2>
; __device__ __forceinline__ void gemm_phase(LAS unsigned char* lds, const int tid, const Gemm g, const Sched& S, const Epi& E) {
;     ...
;     PG8_WAIT_V(0);
;     if constexpr (!ALIGN_EPI) { if (wr == 0) PG8_BAR; }
;     PG8_BAR;
;     __builtin_amdgcn_s_setprio(0);
;     if constexpr (Epi::FUSED_LAST) E.fused(acc, cur, wr, wc, fr, fq, lds, wid, lane);
.LBB0_1168:
	v_mov_b32_e32 v228, 0x358637bd
	v_mov_b32_e32 v229, 0x260
	v_mov_b32_e32 v230, 0x3727c5ac
	v_mov_b32_e32 v231, 0x7ff
	v_mov_b32_e32 v232, 0xff
	v_mov_b32_e32 v233, 0x800
	v_mov_b32_e32 v234, 0x100
	v_mov_b32_e32 v235, 0x7f800000
	v_mov_b32_e32 v236, 0x7fc00000
	v_mov_b32_e32 v237, 0xff800000
	v_mov_b32_e32 v238, 0x600
	v_mov_b32_e32 v239, 0x42800000
	v_not_b32_e32 v240, 63
	v_mov_b32_e32 v241, 0x60000
	v_mov_b64_e32 v[242:243], 0x47
	s_waitcnt vmcnt(0)
	s_barrier
	s_setprio 0
	s_movk_i32 s85, 0x7d7
	s_movk_i32 s86, 0xfe7f
